# GEMM bodies: merged adjacent s_setprio 0/1 pairs into one continuous raised-priority window per MFMA phase
# speedup vs baseline: 1.0065x; 1.0026x over previous
; #define PG8_STAGE(bufoff, gbase, voff) do { _Pragma("unroll") for (int _i = 0; _i < 2; ++_i) \
;         __builtin_amdgcn_global_load_lds((const unsigned*)((const char*)(gbase) + (voff)[_i]), (PG8_LAS unsigned*)(lds + (bufoff) + ldsw + _i * 8192), 16, 0, 0); } while (0)
; #define PG8_LDA(dst, b, h) do { _Pragma("unroll") for (int m = 0; m < 4; ++m) _Pragma("unroll") for (int k = 0; k < 2; ++k) dst[m][k] = *(const PG8_LAS bf16x8*)(lds + PG8_SA(b, h) + aoff + m * 2048 + k * 1024); } while (0)
; #define PG8_LDB(dst, b, h) do { _Pragma("unroll") for (int n = 0; n < 2; ++n) _Pragma("unroll") for (int k = 0; k < 2; ++k) dst[n][k] = *(const PG8_LAS bf16x8*)(lds + PG8_SB(b, h) + boff + n * 2048 + k * 1024); } while (0)
; #define PG8_MMA(ai, bj, At, Bt) do { __builtin_amdgcn_s_setprio(1); _Pragma("unroll") for (int m = 0; m < 4; ++m) _Pragma("unroll") for (int n = 0; n < 2; ++n) _Pragma("unroll") for (int k = 0; k < 2; ++k) \
;         acc[ai][bj][m][n] = __builtin_amdgcn_mfma_f32_16x16x32_bf16(Bt[n][k], At[m][k], acc[ai][bj][m][n], 0, 0, 0); __builtin_amdgcn_s_setprio(0); } while (0)
; #define PG8_WAIT_V(n) asm volatile("s_waitcnt vmcnt(" #n ")" ::: "memory")
; #define PG8_WAIT_L(n) asm volatile("s_waitcnt lgkmcnt(" #n ")" ::: "memory")
; #define PG8_BAR __builtin_amdgcn_s_barrier()
; #define PG8_SCHED __builtin_amdgcn_sched_barrier(0)
; template <class Epi, class Sched, bool ALIGN_EPI = false, bool SP2 = false>
; __device__ __forceinline__ void gemm_phase(PG8_LAS unsigned char* lds, const Gemm g, const Sched& S, const Epi& E, int wave_sgpr) {
;     ...
;             PG8_LDB(B0, 0, 0); PG8_LDB(B1, 0, 1); PG8_SCHED; PG8_LDA(At, 0, 0); PG8_STAGE(PG8_SA(1, 1), a1 + hstepA, voffA);
;             PG8_WAIT_V(8); PG8_WAIT_L(0); PG8_BAR; PG8_MMA(0, 0, At, B0); PG8_MMA(0, 1, At, B1); PG8_BAR; PG8_SCHED;
;             PG8_LDA(At, 0, 1); PG8_STAGE(PG8_SB(0, 0), b2, voffB); PG8_STAGE(PG8_SB(0, 1), b2 + hstepB, voffB); PG8_STAGE(PG8_SA(0, 0), a2, voffA);
.LBB0_298:
	s_add_u32 s10, s6, 0xfffc0080
	s_addc_u32 s11, s7, -1
	s_add_i32 s55, 0, 0x10000
	s_cmp_eq_u32 s54, 12
	s_cselect_b32 s13, s5, s11
	s_cselect_b32 s12, s9, s10
	s_cselect_b32 s11, s20, s53
	s_cselect_b32 s10, s23, s52
	s_add_i32 s59, 0, 0x14000
	v_add_u32_e32 v140, s55, v219
	v_add_u32_e32 v156, s59, v219
	ds_read_b128 v[128:131], v140
	ds_read_b128 v[132:135], v140 offset:1024
	ds_read_b128 v[136:139], v140 offset:2048
	ds_read_b128 v[140:143], v140 offset:3072
	ds_read_b128 v[144:147], v156
	ds_read_b128 v[148:151], v156 offset:1024
	ds_read_b128 v[152:155], v156 offset:2048
	ds_read_b128 v[174:177], v156 offset:3072
	v_lshl_add_u64 v[202:203], s[6:7], 0, v[170:171]
	s_add_i32 m0, s43, 0xc000
	ds_read_b128 v[178:181], v220
	ds_read_b128 v[182:185], v220 offset:1024
	ds_read_b128 v[186:189], v220 offset:2048
	ds_read_b128 v[190:193], v220 offset:3072
	ds_read_b128 v[194:197], v220 offset:4096
	ds_read_b128 v[198:201], v220 offset:5120
	ds_read_b128 v[206:209], v220 offset:6144
	ds_read_b128 v[210:213], v220 offset:7168
	global_load_lds_dwordx4 v[202:203], off
	v_lshl_add_u64 v[202:203], s[6:7], 0, v[172:173]
	s_add_i32 m0, s43, 0xe000
	s_nop 0
	global_load_lds_dwordx4 v[202:203], off
	s_waitcnt vmcnt(8)
	s_waitcnt lgkmcnt(0)
	s_barrier
	s_setprio 1
	s_waitcnt lgkmcnt(0)
	v_mfma_f32_16x16x32_bf16 v[124:127], v[128:131], v[178:181], v[124:127]
	v_mfma_f32_16x16x32_bf16 v[120:123], v[136:139], v[178:181], v[120:123]
	v_mfma_f32_16x16x32_bf16 v[108:111], v[128:131], v[186:189], v[108:111]
	v_mfma_f32_16x16x32_bf16 v[104:107], v[136:139], v[186:189], v[104:107]
	v_mfma_f32_16x16x32_bf16 v[92:95], v[128:131], v[194:197], v[92:95]
	v_mfma_f32_16x16x32_bf16 v[88:91], v[136:139], v[194:197], v[88:91]
	v_mfma_f32_16x16x32_bf16 v[76:79], v[128:131], v[206:209], v[76:79]
	v_mfma_f32_16x16x32_bf16 v[72:75], v[136:139], v[206:209], v[72:75]
	v_mfma_f32_16x16x32_bf16 v[124:127], v[132:135], v[182:185], v[124:127]
	v_mfma_f32_16x16x32_bf16 v[120:123], v[140:143], v[182:185], v[120:123]
	v_mfma_f32_16x16x32_bf16 v[108:111], v[132:135], v[190:193], v[108:111]
	v_mfma_f32_16x16x32_bf16 v[104:107], v[140:143], v[190:193], v[104:107]
	v_mfma_f32_16x16x32_bf16 v[92:95], v[132:135], v[198:201], v[92:95]
	v_mfma_f32_16x16x32_bf16 v[88:91], v[140:143], v[198:201], v[88:91]
	v_mfma_f32_16x16x32_bf16 v[76:79], v[132:135], v[210:213], v[76:79]
	v_mfma_f32_16x16x32_bf16 v[72:75], v[140:143], v[210:213], v[72:75]
	v_mfma_f32_16x16x32_bf16 v[116:119], v[144:147], v[178:181], v[116:119]
	v_mfma_f32_16x16x32_bf16 v[112:115], v[152:155], v[178:181], v[112:115]
	v_mfma_f32_16x16x32_bf16 v[100:103], v[144:147], v[186:189], v[100:103]
	v_mfma_f32_16x16x32_bf16 v[96:99], v[152:155], v[186:189], v[96:99]
	v_mfma_f32_16x16x32_bf16 v[84:87], v[144:147], v[194:197], v[84:87]
	v_mfma_f32_16x16x32_bf16 v[80:83], v[152:155], v[194:197], v[80:83]
	v_mfma_f32_16x16x32_bf16 v[68:71], v[144:147], v[206:209], v[68:71]
	v_mfma_f32_16x16x32_bf16 v[64:67], v[152:155], v[206:209], v[64:67]
	v_mfma_f32_16x16x32_bf16 v[116:119], v[148:151], v[182:185], v[116:119]
	v_mfma_f32_16x16x32_bf16 v[112:115], v[174:177], v[182:185], v[112:115]
	v_mfma_f32_16x16x32_bf16 v[100:103], v[148:151], v[190:193], v[100:103]
	v_mfma_f32_16x16x32_bf16 v[96:99], v[174:177], v[190:193], v[96:99]
	v_mfma_f32_16x16x32_bf16 v[84:87], v[148:151], v[198:201], v[84:87]
	v_mfma_f32_16x16x32_bf16 v[80:83], v[174:177], v[198:201], v[80:83]
	v_mfma_f32_16x16x32_bf16 v[68:71], v[148:151], v[210:213], v[68:71]
	v_mfma_f32_16x16x32_bf16 v[64:67], v[174:177], v[210:213], v[64:67]
	s_setprio 0
	s_barrier
	s_add_i32 s55, s55, s31
	v_lshl_add_u64 v[202:203], s[10:11], 0, v[164:165]
	s_mov_b32 m0, s55
	ds_read_b128 v[178:181], v220 offset:16384
	ds_read_b128 v[182:185], v220 offset:17408
	ds_read_b128 v[186:189], v220 offset:18432
	ds_read_b128 v[190:193], v220 offset:19456
	ds_read_b128 v[194:197], v220 offset:20480
	ds_read_b128 v[198:201], v220 offset:21504
	ds_read_b128 v[206:209], v220 offset:22528
	ds_read_b128 v[210:213], v220 offset:23552
	global_load_lds_dwordx4 v[202:203], off
	s_add_i32 m0, s55, 0x2000
	s_add_u32 s56, s10, 0x40000
	v_lshl_add_u64 v[222:223], s[10:11], 0, v[168:169]
	s_addc_u32 s57, s11, 0
	s_add_i32 s55, s59, s31
	global_load_lds_dwordx4 v[222:223], off
	v_lshl_add_u64 v[224:225], s[56:57], 0, v[164:165]
	s_mov_b32 m0, s55
	v_lshl_add_u64 v[226:227], s[12:13], 0, v[166:167]
	global_load_lds_dwordx4 v[224:225], off
	v_lshl_add_u64 v[224:225], s[56:57], 0, v[168:169]
	s_add_i32 m0, s55, 0x2000
	s_nop 0
	global_load_lds_dwordx4 v[224:225], off
	v_lshl_add_u64 v[224:225], s[12:13], 0, v[162:163]
	s_mov_b32 m0, s43
	s_nop 0
	global_load_lds_dwordx4 v[224:225], off
	s_mov_b32 m0, s24
	s_nop 0
	global_load_lds_dwordx4 v[226:227], off
	s_waitcnt vmcnt(8)
	s_waitcnt lgkmcnt(0)
	s_barrier
; #define PG8_STAGE(bufoff, gbase, voff) do { _Pragma("unroll") for (int _i = 0; _i < 2; ++_i) \
;         __builtin_amdgcn_global_load_lds((const unsigned*)((const char*)(gbase) + (voff)[_i]), (PG8_LAS unsigned*)(lds + (bufoff) + ldsw + _i * 8192), 16, 0, 0); } while (0)
; #define PG8_LDA(dst, b, h) do { _Pragma("unroll") for (int m = 0; m < 4; ++m) _Pragma("unroll") for (int k = 0; k < 2; ++k) dst[m][k] = *(const PG8_LAS bf16x8*)(lds + PG8_SA(b, h) + aoff + m * 2048 + k * 1024); } while (0)
; #define PG8_LDB(dst, b, h) do { _Pragma("unroll") for (int n = 0; n < 2; ++n) _Pragma("unroll") for (int k = 0; k < 2; ++k) dst[n][k] = *(const PG8_LAS bf16x8*)(lds + PG8_SB(b, h) + boff + n * 2048 + k * 1024); } while (0)
; #define PG8_MMA(ai, bj, At, Bt) do { __builtin_amdgcn_s_setprio(1); _Pragma("unroll") for (int m = 0; m < 4; ++m) _Pragma("unroll") for (int n = 0; n < 2; ++n) _Pragma("unroll") for (int k = 0; k < 2; ++k) \
;         acc[ai][bj][m][n] = __builtin_amdgcn_mfma_f32_16x16x32_bf16(Bt[n][k], At[m][k], acc[ai][bj][m][n], 0, 0, 0); __builtin_amdgcn_s_setprio(0); } while (0)
; #define PG8_WAIT_V(n) asm volatile("s_waitcnt vmcnt(" #n ")" ::: "memory")
; #define PG8_WAIT_L(n) asm volatile("s_waitcnt lgkmcnt(" #n ")" ::: "memory")
; #define PG8_BAR __builtin_amdgcn_s_barrier()
; #define PG8_SCHED __builtin_amdgcn_sched_barrier(0)
; template <class Epi, class Sched, bool ALIGN_EPI = false, bool SP2 = false>
; __device__ __forceinline__ void gemm_phase(PG8_LAS unsigned char* lds, const Gemm g, const Sched& S, const Epi& E, int wave_sgpr) {
;     ...
;             PG8_WAIT_V(8); PG8_WAIT_L(0); PG8_BAR; PG8_MMA(1, 0, At, B0); PG8_MMA(1, 1, At, B1); PG8_BAR; PG8_SCHED;
;             PG8_LDB(B0, 1, 0); PG8_LDB(B1, 1, 1); PG8_SCHED; PG8_LDA(At, 1, 0); PG8_STAGE(PG8_SA(0, 1), a2 + hstepA, voffA);
;             PG8_WAIT_V(8); PG8_WAIT_L(0); PG8_BAR; PG8_MMA(0, 0, At, B0); PG8_MMA(0, 1, At, B1); PG8_BAR; PG8_SCHED;
	s_setprio 1
	s_waitcnt lgkmcnt(0)
	v_mfma_f32_16x16x32_bf16 v[60:63], v[128:131], v[178:181], v[60:63]
	v_mfma_f32_16x16x32_bf16 v[56:59], v[136:139], v[178:181], v[56:59]
	v_mfma_f32_16x16x32_bf16 v[44:47], v[128:131], v[186:189], v[44:47]
	v_mfma_f32_16x16x32_bf16 v[40:43], v[136:139], v[186:189], v[40:43]
	v_mfma_f32_16x16x32_bf16 v[28:31], v[128:131], v[194:197], v[28:31]
	v_mfma_f32_16x16x32_bf16 v[24:27], v[136:139], v[194:197], v[24:27]
	v_mfma_f32_16x16x32_bf16 v[12:15], v[128:131], v[206:209], v[12:15]
	v_mfma_f32_16x16x32_bf16 v[8:11], v[136:139], v[206:209], v[8:11]
	v_mfma_f32_16x16x32_bf16 v[60:63], v[132:135], v[182:185], v[60:63]
	v_mfma_f32_16x16x32_bf16 v[56:59], v[140:143], v[182:185], v[56:59]
	v_mfma_f32_16x16x32_bf16 v[44:47], v[132:135], v[190:193], v[44:47]
	v_mfma_f32_16x16x32_bf16 v[40:43], v[140:143], v[190:193], v[40:43]
	v_mfma_f32_16x16x32_bf16 v[28:31], v[132:135], v[198:201], v[28:31]
	v_mfma_f32_16x16x32_bf16 v[24:27], v[140:143], v[198:201], v[24:27]
	v_mfma_f32_16x16x32_bf16 v[12:15], v[132:135], v[210:213], v[12:15]
	v_mfma_f32_16x16x32_bf16 v[8:11], v[140:143], v[210:213], v[8:11]
	v_mfma_f32_16x16x32_bf16 v[52:55], v[144:147], v[178:181], v[52:55]
	v_mfma_f32_16x16x32_bf16 v[48:51], v[152:155], v[178:181], v[48:51]
	v_mfma_f32_16x16x32_bf16 v[36:39], v[144:147], v[186:189], v[36:39]
	v_mfma_f32_16x16x32_bf16 v[32:35], v[152:155], v[186:189], v[32:35]
	v_mfma_f32_16x16x32_bf16 v[20:23], v[144:147], v[194:197], v[20:23]
	v_mfma_f32_16x16x32_bf16 v[16:19], v[152:155], v[194:197], v[16:19]
	v_mfma_f32_16x16x32_bf16 v[4:7], v[144:147], v[206:209], v[4:7]
	v_mfma_f32_16x16x32_bf16 v[0:3], v[152:155], v[206:209], v[0:3]
	v_mfma_f32_16x16x32_bf16 v[52:55], v[148:151], v[182:185], v[52:55]
	v_mfma_f32_16x16x32_bf16 v[48:51], v[174:177], v[182:185], v[48:51]
	v_mfma_f32_16x16x32_bf16 v[36:39], v[148:151], v[190:193], v[36:39]
	v_mfma_f32_16x16x32_bf16 v[32:35], v[174:177], v[190:193], v[32:35]
	v_mfma_f32_16x16x32_bf16 v[20:23], v[148:151], v[198:201], v[20:23]
	v_mfma_f32_16x16x32_bf16 v[16:19], v[174:177], v[198:201], v[16:19]
	v_mfma_f32_16x16x32_bf16 v[4:7], v[148:151], v[210:213], v[4:7]
	v_mfma_f32_16x16x32_bf16 v[0:3], v[174:177], v[210:213], v[0:3]
	s_setprio 0
	s_barrier
	s_add_i32 s55, 0, 0x18000
	s_add_i32 s56, 0, 0x1c000
	v_add_u32_e32 v140, s55, v219
	v_add_u32_e32 v156, s56, v219
	ds_read_b128 v[128:131], v140
	ds_read_b128 v[132:135], v140 offset:1024
	ds_read_b128 v[136:139], v140 offset:2048
	ds_read_b128 v[140:143], v140 offset:3072
	ds_read_b128 v[144:147], v156
	ds_read_b128 v[148:151], v156 offset:1024
	ds_read_b128 v[152:155], v156 offset:2048
	ds_read_b128 v[174:177], v156 offset:3072
	s_add_u32 s12, s12, 0x40000
	s_addc_u32 s13, s13, 0
	s_mov_b32 m0, s25
	v_lshl_add_u64 v[228:229], s[12:13], 0, v[162:163]
	ds_read_b128 v[178:181], v220 offset:32768
	ds_read_b128 v[182:185], v220 offset:33792
	ds_read_b128 v[186:189], v220 offset:34816
	ds_read_b128 v[190:193], v220 offset:35840
	ds_read_b128 v[194:197], v220 offset:36864
	ds_read_b128 v[198:201], v220 offset:37888
	ds_read_b128 v[206:209], v220 offset:38912
	ds_read_b128 v[210:213], v220 offset:39936
	global_load_lds_dwordx4 v[228:229], off
	v_lshl_add_u64 v[228:229], s[12:13], 0, v[166:167]
	s_mov_b32 m0, s18
	s_nop 0
	global_load_lds_dwordx4 v[228:229], off
	s_waitcnt vmcnt(8)
	s_waitcnt lgkmcnt(0)
	s_barrier
	s_setprio 1
	s_waitcnt lgkmcnt(0)
	v_mfma_f32_16x16x32_bf16 v[124:127], v[128:131], v[178:181], v[124:127]
	v_mfma_f32_16x16x32_bf16 v[120:123], v[136:139], v[178:181], v[120:123]
	v_mfma_f32_16x16x32_bf16 v[108:111], v[128:131], v[186:189], v[108:111]
	v_mfma_f32_16x16x32_bf16 v[104:107], v[136:139], v[186:189], v[104:107]
	v_mfma_f32_16x16x32_bf16 v[92:95], v[128:131], v[194:197], v[92:95]
	v_mfma_f32_16x16x32_bf16 v[88:91], v[136:139], v[194:197], v[88:91]
	v_mfma_f32_16x16x32_bf16 v[76:79], v[128:131], v[206:209], v[76:79]
	v_mfma_f32_16x16x32_bf16 v[72:75], v[136:139], v[206:209], v[72:75]
	v_mfma_f32_16x16x32_bf16 v[124:127], v[132:135], v[182:185], v[124:127]
	v_mfma_f32_16x16x32_bf16 v[120:123], v[140:143], v[182:185], v[120:123]
	v_mfma_f32_16x16x32_bf16 v[108:111], v[132:135], v[190:193], v[108:111]
	v_mfma_f32_16x16x32_bf16 v[104:107], v[140:143], v[190:193], v[104:107]
	v_mfma_f32_16x16x32_bf16 v[92:95], v[132:135], v[198:201], v[92:95]
	v_mfma_f32_16x16x32_bf16 v[88:91], v[140:143], v[198:201], v[88:91]
	v_mfma_f32_16x16x32_bf16 v[76:79], v[132:135], v[210:213], v[76:79]
	v_mfma_f32_16x16x32_bf16 v[72:75], v[140:143], v[210:213], v[72:75]
	v_mfma_f32_16x16x32_bf16 v[116:119], v[144:147], v[178:181], v[116:119]
	v_mfma_f32_16x16x32_bf16 v[112:115], v[152:155], v[178:181], v[112:115]
	v_mfma_f32_16x16x32_bf16 v[100:103], v[144:147], v[186:189], v[100:103]
	v_mfma_f32_16x16x32_bf16 v[96:99], v[152:155], v[186:189], v[96:99]
	v_mfma_f32_16x16x32_bf16 v[84:87], v[144:147], v[194:197], v[84:87]
	v_mfma_f32_16x16x32_bf16 v[80:83], v[152:155], v[194:197], v[80:83]
	v_mfma_f32_16x16x32_bf16 v[68:71], v[144:147], v[206:209], v[68:71]
	v_mfma_f32_16x16x32_bf16 v[64:67], v[152:155], v[206:209], v[64:67]
	v_mfma_f32_16x16x32_bf16 v[116:119], v[148:151], v[182:185], v[116:119]
	v_mfma_f32_16x16x32_bf16 v[112:115], v[174:177], v[182:185], v[112:115]
	v_mfma_f32_16x16x32_bf16 v[100:103], v[148:151], v[190:193], v[100:103]
	v_mfma_f32_16x16x32_bf16 v[96:99], v[174:177], v[190:193], v[96:99]
	v_mfma_f32_16x16x32_bf16 v[84:87], v[148:151], v[198:201], v[84:87]
	v_mfma_f32_16x16x32_bf16 v[80:83], v[174:177], v[198:201], v[80:83]
	v_mfma_f32_16x16x32_bf16 v[68:71], v[148:151], v[210:213], v[68:71]
	v_mfma_f32_16x16x32_bf16 v[64:67], v[174:177], v[210:213], v[64:67]
	s_setprio 0
	s_barrier
; #define PG8_STAGE(bufoff, gbase, voff) do { _Pragma("unroll") for (int _i = 0; _i < 2; ++_i) \
;         __builtin_amdgcn_global_load_lds((const unsigned*)((const char*)(gbase) + (voff)[_i]), (PG8_LAS unsigned*)(lds + (bufoff) + ldsw + _i * 8192), 16, 0, 0); } while (0)
; #define PG8_LDA(dst, b, h) do { _Pragma("unroll") for (int m = 0; m < 4; ++m) _Pragma("unroll") for (int k = 0; k < 2; ++k) dst[m][k] = *(const PG8_LAS bf16x8*)(lds + PG8_SA(b, h) + aoff + m * 2048 + k * 1024); } while (0)
; #define PG8_MMA(ai, bj, At, Bt) do { __builtin_amdgcn_s_setprio(1); _Pragma("unroll") for (int m = 0; m < 4; ++m) _Pragma("unroll") for (int n = 0; n < 2; ++n) _Pragma("unroll") for (int k = 0; k < 2; ++k) \
;         acc[ai][bj][m][n] = __builtin_amdgcn_mfma_f32_16x16x32_bf16(Bt[n][k], At[m][k], acc[ai][bj][m][n], 0, 0, 0); __builtin_amdgcn_s_setprio(0); } while (0)
; #define PG8_WAIT_V(n) asm volatile("s_waitcnt vmcnt(" #n ")" ::: "memory")
; #define PG8_WAIT_L(n) asm volatile("s_waitcnt lgkmcnt(" #n ")" ::: "memory")
; #define PG8_BAR __builtin_amdgcn_s_barrier()
; #define PG8_SCHED __builtin_amdgcn_sched_barrier(0)
; template <class Epi, class Sched, bool ALIGN_EPI = false, bool SP2 = false>
; __device__ __forceinline__ void gemm_phase(PG8_LAS unsigned char* lds, const Gemm g, const Sched& S, const Epi& E, int wave_sgpr) {
;     ...
;         for (int t = 0; t < nt; t += 2) {
;             const bool last = (t == nt - 2);
;             const char* a1 = cA + (size_t)(t + 1) * kstep;
;             const char* a2 = last ? nA : cA + (size_t)(t + 2) * kstep; const char* b2 = last ? nB : cB + (size_t)(t + 2) * kstep;
;     ...
;             PG8_LDA(At, 1, 1); PG8_STAGE(PG8_SB(1, 0), b3, voffB); PG8_STAGE(PG8_SB(1, 1), b3 + hstepB, voffB); PG8_STAGE(PG8_SA(1, 0), a3, voffA);
;             PG8_WAIT_V(8); PG8_WAIT_L(0); PG8_BAR; PG8_MMA(1, 0, At, B0); PG8_MMA(1, 1, At, B1); PG8_BAR; PG8_SCHED;
	s_add_i32 s12, s55, s31
	v_lshl_add_u64 v[202:203], v[202:203], 0, s[44:45]
	s_mov_b32 m0, s12
	ds_read_b128 v[178:181], v220 offset:49152
	ds_read_b128 v[182:185], v220 offset:50176
	ds_read_b128 v[186:189], v220 offset:51200
	ds_read_b128 v[190:193], v220 offset:52224
	ds_read_b128 v[194:197], v220 offset:53248
	ds_read_b128 v[198:201], v220 offset:54272
	ds_read_b128 v[206:209], v220 offset:55296
	ds_read_b128 v[210:213], v220 offset:56320
	global_load_lds_dwordx4 v[202:203], off
	s_add_i32 m0, s12, 0x2000
	s_add_u32 s10, s10, 0x40080
	v_lshl_add_u64 v[202:203], v[222:223], 0, s[44:45]
	s_addc_u32 s11, s11, 0
	s_add_i32 s12, s56, s31
	global_load_lds_dwordx4 v[202:203], off
	v_lshl_add_u64 v[202:203], s[10:11], 0, v[164:165]
	s_mov_b32 m0, s12
	s_nop 0
	global_load_lds_dwordx4 v[202:203], off
	v_lshl_add_u64 v[202:203], s[10:11], 0, v[168:169]
	s_add_i32 m0, s12, 0x2000
	s_nop 0
	global_load_lds_dwordx4 v[202:203], off
	v_lshl_add_u64 v[202:203], v[224:225], 0, s[44:45]
	s_mov_b32 m0, s38
	s_nop 0
	global_load_lds_dwordx4 v[202:203], off
	v_lshl_add_u64 v[202:203], v[226:227], 0, s[44:45]
	s_mov_b32 m0, s39
	s_nop 0
	global_load_lds_dwordx4 v[202:203], off
	s_waitcnt vmcnt(8)
	s_waitcnt lgkmcnt(0)
	s_barrier
	s_setprio 1
	s_waitcnt lgkmcnt(0)
	v_mfma_f32_16x16x32_bf16 v[60:63], v[128:131], v[178:181], v[60:63]
	v_mfma_f32_16x16x32_bf16 v[56:59], v[136:139], v[178:181], v[56:59]
	v_mfma_f32_16x16x32_bf16 v[44:47], v[128:131], v[186:189], v[44:47]
	v_mfma_f32_16x16x32_bf16 v[40:43], v[136:139], v[186:189], v[40:43]
	v_mfma_f32_16x16x32_bf16 v[28:31], v[128:131], v[194:197], v[28:31]
	v_mfma_f32_16x16x32_bf16 v[24:27], v[136:139], v[194:197], v[24:27]
	v_mfma_f32_16x16x32_bf16 v[12:15], v[128:131], v[206:209], v[12:15]
	v_mfma_f32_16x16x32_bf16 v[8:11], v[136:139], v[206:209], v[8:11]
	v_mfma_f32_16x16x32_bf16 v[60:63], v[132:135], v[182:185], v[60:63]
	v_mfma_f32_16x16x32_bf16 v[56:59], v[140:143], v[182:185], v[56:59]
	v_mfma_f32_16x16x32_bf16 v[44:47], v[132:135], v[190:193], v[44:47]
	v_mfma_f32_16x16x32_bf16 v[40:43], v[140:143], v[190:193], v[40:43]
	v_mfma_f32_16x16x32_bf16 v[28:31], v[132:135], v[198:201], v[28:31]
	v_mfma_f32_16x16x32_bf16 v[24:27], v[140:143], v[198:201], v[24:27]
	v_mfma_f32_16x16x32_bf16 v[12:15], v[132:135], v[210:213], v[12:15]
	v_mfma_f32_16x16x32_bf16 v[8:11], v[140:143], v[210:213], v[8:11]
	v_mfma_f32_16x16x32_bf16 v[52:55], v[144:147], v[178:181], v[52:55]
	v_mfma_f32_16x16x32_bf16 v[48:51], v[152:155], v[178:181], v[48:51]
	v_mfma_f32_16x16x32_bf16 v[36:39], v[144:147], v[186:189], v[36:39]
	v_mfma_f32_16x16x32_bf16 v[32:35], v[152:155], v[186:189], v[32:35]
	v_mfma_f32_16x16x32_bf16 v[20:23], v[144:147], v[194:197], v[20:23]
	v_mfma_f32_16x16x32_bf16 v[16:19], v[152:155], v[194:197], v[16:19]
	v_mfma_f32_16x16x32_bf16 v[4:7], v[144:147], v[206:209], v[4:7]
	v_mfma_f32_16x16x32_bf16 v[0:3], v[152:155], v[206:209], v[0:3]
	v_mfma_f32_16x16x32_bf16 v[52:55], v[148:151], v[182:185], v[52:55]
	v_mfma_f32_16x16x32_bf16 v[48:51], v[174:177], v[182:185], v[48:51]
	v_mfma_f32_16x16x32_bf16 v[36:39], v[148:151], v[190:193], v[36:39]
	v_mfma_f32_16x16x32_bf16 v[32:35], v[174:177], v[190:193], v[32:35]
	v_mfma_f32_16x16x32_bf16 v[20:23], v[148:151], v[198:201], v[20:23]
	v_mfma_f32_16x16x32_bf16 v[16:19], v[174:177], v[198:201], v[16:19]
	v_mfma_f32_16x16x32_bf16 v[4:7], v[148:151], v[210:213], v[4:7]
	v_mfma_f32_16x16x32_bf16 v[0:3], v[174:177], v[210:213], v[0:3]
	s_setprio 0
	s_barrier
	s_add_i32 s54, s54, 2
	s_add_u32 s6, s6, 0x100
	s_addc_u32 s7, s7, 0
	s_add_u32 s52, s52, 0x100
	s_addc_u32 s53, s53, 0
	s_cmp_gt_u32 s54, 13
	s_cbranch_scc0 .LBB0_298
	s_and_b64 vcc, exec, s[50:51]
	s_cbranch_vccz .LBB0_301
	s_barrier

; #define PG8_STAGE(bufoff, gbase, voff) do { _Pragma("unroll") for (int _i = 0; _i < 2; ++_i) \
;         __builtin_amdgcn_global_load_lds((const unsigned*)((const char*)(gbase) + (voff)[_i]), (PG8_LAS unsigned*)(lds + (bufoff) + ldsw + _i * 8192), 16, 0, 0); } while (0)
; #define PG8_LDA(dst, b, h) do { _Pragma("unroll") for (int m = 0; m < 4; ++m) _Pragma("unroll") for (int k = 0; k < 2; ++k) dst[m][k] = *(const PG8_LAS bf16x8*)(lds + PG8_SA(b, h) + aoff + m * 2048 + k * 1024); } while (0)
; #define PG8_LDB(dst, b, h) do { _Pragma("unroll") for (int n = 0; n < 2; ++n) _Pragma("unroll") for (int k = 0; k < 2; ++k) dst[n][k] = *(const PG8_LAS bf16x8*)(lds + PG8_SB(b, h) + boff + n * 2048 + k * 1024); } while (0)
; #define PG8_MMA(ai, bj, At, Bt) do { __builtin_amdgcn_s_setprio(1); _Pragma("unroll") for (int m = 0; m < 4; ++m) _Pragma("unroll") for (int n = 0; n < 2; ++n) _Pragma("unroll") for (int k = 0; k < 2; ++k) \
;         acc[ai][bj][m][n] = __builtin_amdgcn_mfma_f32_16x16x32_bf16(Bt[n][k], At[m][k], acc[ai][bj][m][n], 0, 0, 0); __builtin_amdgcn_s_setprio(0); } while (0)
; #define PG8_WAIT_V(n) asm volatile("s_waitcnt vmcnt(" #n ")" ::: "memory")
; #define PG8_WAIT_L(n) asm volatile("s_waitcnt lgkmcnt(" #n ")" ::: "memory")
; #define PG8_BAR __builtin_amdgcn_s_barrier()
; #define PG8_SCHED __builtin_amdgcn_sched_barrier(0)
; template <class Epi, class Sched, bool ALIGN_EPI = false, bool SP2 = false>
; __device__ __forceinline__ void gemm_phase(PG8_LAS unsigned char* lds, const Gemm g, const Sched& S, const Epi& E, int wave_sgpr) {
;     ...
;             PG8_LDB(B0, 0, 0); PG8_LDB(B1, 0, 1); PG8_SCHED; PG8_LDA(At, 0, 0); PG8_STAGE(PG8_SA(1, 1), a1 + hstepA, voffA);
;             PG8_WAIT_V(8); PG8_WAIT_L(0); PG8_BAR; PG8_MMA(0, 0, At, B0); PG8_MMA(0, 1, At, B1); PG8_BAR; PG8_SCHED;
;             PG8_LDA(At, 0, 1); PG8_STAGE(PG8_SB(0, 0), b2, voffB); PG8_STAGE(PG8_SB(0, 1), b2 + hstepB, voffB); PG8_STAGE(PG8_SA(0, 0), a2, voffA);
.LBB0_1077:
	ds_read_b128 v[56:59], v165
	ds_read_b128 v[60:63], v165 offset:1024
	ds_read_b128 v[72:75], v165 offset:2048
	ds_read_b128 v[76:79], v165 offset:3072
	ds_read_b128 v[156:159], v166
	ds_read_b128 v[168:171], v166 offset:1024
	ds_read_b128 v[172:175], v166 offset:2048
	ds_read_b128 v[176:179], v166 offset:3072
	s_add_u32 s24, s22, 0xfffbf880
	s_addc_u32 s25, s23, -1
	s_cmp_eq_u32 s61, 28
	s_cselect_b32 s27, s19, s25
	s_cselect_b32 s26, s18, s24
	s_cselect_b32 s25, s57, s60
	s_cselect_b32 s24, s58, s59
	s_mov_b32 m0, s47
	v_lshl_add_u64 v[160:161], s[22:23], 0, v[152:153]
	ds_read_b128 v[180:183], v167
	ds_read_b128 v[184:187], v167 offset:1024
	ds_read_b128 v[188:191], v167 offset:2048
	ds_read_b128 v[192:195], v167 offset:3072
	ds_read_b128 v[196:199], v167 offset:4096
	ds_read_b128 v[200:203], v167 offset:5120
	ds_read_b128 v[204:207], v167 offset:6144
	ds_read_b128 v[208:211], v167 offset:7168
	global_load_lds_dwordx4 v[160:161], off
	v_lshl_add_u64 v[160:161], s[22:23], 0, v[154:155]
	s_mov_b32 m0, s48
	s_nop 0
	global_load_lds_dwordx4 v[160:161], off
	s_waitcnt vmcnt(8)
	s_waitcnt lgkmcnt(0)
	s_barrier
	s_setprio 1
	s_waitcnt lgkmcnt(0)
	v_mfma_f32_16x16x32_bf16 v[140:143], v[56:59], v[180:183], v[140:143]
	v_mfma_f32_16x16x32_bf16 v[136:139], v[72:75], v[180:183], v[136:139]
	v_mfma_f32_16x16x32_bf16 v[124:127], v[56:59], v[188:191], v[124:127]
	v_mfma_f32_16x16x32_bf16 v[120:123], v[72:75], v[188:191], v[120:123]
	v_mfma_f32_16x16x32_bf16 v[108:111], v[56:59], v[196:199], v[108:111]
	v_mfma_f32_16x16x32_bf16 v[104:107], v[72:75], v[196:199], v[104:107]
	v_mfma_f32_16x16x32_bf16 v[92:95], v[56:59], v[204:207], v[92:95]
	v_mfma_f32_16x16x32_bf16 v[88:91], v[72:75], v[204:207], v[88:91]
	v_mfma_f32_16x16x32_bf16 v[140:143], v[60:63], v[184:187], v[140:143]
	v_mfma_f32_16x16x32_bf16 v[136:139], v[76:79], v[184:187], v[136:139]
	v_mfma_f32_16x16x32_bf16 v[124:127], v[60:63], v[192:195], v[124:127]
	v_mfma_f32_16x16x32_bf16 v[120:123], v[76:79], v[192:195], v[120:123]
	v_mfma_f32_16x16x32_bf16 v[108:111], v[60:63], v[200:203], v[108:111]
	v_mfma_f32_16x16x32_bf16 v[104:107], v[76:79], v[200:203], v[104:107]
	v_mfma_f32_16x16x32_bf16 v[92:95], v[60:63], v[208:211], v[92:95]
	v_mfma_f32_16x16x32_bf16 v[88:91], v[76:79], v[208:211], v[88:91]
	v_mfma_f32_16x16x32_bf16 v[132:135], v[156:159], v[180:183], v[132:135]
	v_mfma_f32_16x16x32_bf16 v[128:131], v[172:175], v[180:183], v[128:131]
	v_mfma_f32_16x16x32_bf16 v[116:119], v[156:159], v[188:191], v[116:119]
	v_mfma_f32_16x16x32_bf16 v[112:115], v[172:175], v[188:191], v[112:115]
	v_mfma_f32_16x16x32_bf16 v[100:103], v[156:159], v[196:199], v[100:103]
	v_mfma_f32_16x16x32_bf16 v[96:99], v[172:175], v[196:199], v[96:99]
	v_mfma_f32_16x16x32_bf16 v[84:87], v[156:159], v[204:207], v[84:87]
	v_mfma_f32_16x16x32_bf16 v[80:83], v[172:175], v[204:207], v[80:83]
	v_mfma_f32_16x16x32_bf16 v[132:135], v[168:171], v[184:187], v[132:135]
	v_mfma_f32_16x16x32_bf16 v[128:131], v[176:179], v[184:187], v[128:131]
	v_mfma_f32_16x16x32_bf16 v[116:119], v[168:171], v[192:195], v[116:119]
	v_mfma_f32_16x16x32_bf16 v[112:115], v[176:179], v[192:195], v[112:115]
	v_mfma_f32_16x16x32_bf16 v[100:103], v[168:171], v[200:203], v[100:103]
	v_mfma_f32_16x16x32_bf16 v[96:99], v[176:179], v[200:203], v[96:99]
	v_mfma_f32_16x16x32_bf16 v[84:87], v[168:171], v[208:211], v[84:87]
	v_mfma_f32_16x16x32_bf16 v[80:83], v[176:179], v[208:211], v[80:83]
	s_setprio 0
	s_barrier
	s_mov_b32 m0, s49
	v_lshl_add_u64 v[160:161], s[24:25], 0, v[148:149]
	s_add_u32 s62, s24, 0x80000
	ds_read_b128 v[180:183], v167 offset:16384
	ds_read_b128 v[184:187], v167 offset:17408
	ds_read_b128 v[188:191], v167 offset:18432
	ds_read_b128 v[192:195], v167 offset:19456
	ds_read_b128 v[196:199], v167 offset:20480
	ds_read_b128 v[200:203], v167 offset:21504
	ds_read_b128 v[204:207], v167 offset:22528
	ds_read_b128 v[208:211], v167 offset:23552
	global_load_lds_dwordx4 v[160:161], off
	v_lshl_add_u64 v[212:213], s[24:25], 0, v[144:145]
	s_mov_b32 m0, s50
	s_addc_u32 s63, s25, 0
	global_load_lds_dwordx4 v[212:213], off
	v_lshl_add_u64 v[214:215], s[62:63], 0, v[148:149]
	s_mov_b32 m0, s51
	v_lshl_add_u64 v[216:217], s[26:27], 0, v[146:147]
	global_load_lds_dwordx4 v[214:215], off
	v_lshl_add_u64 v[214:215], s[62:63], 0, v[144:145]
	s_mov_b32 m0, s52
	s_nop 0
	global_load_lds_dwordx4 v[214:215], off
	v_lshl_add_u64 v[214:215], s[26:27], 0, v[150:151]
	s_mov_b32 m0, s3
	s_nop 0
	global_load_lds_dwordx4 v[214:215], off
	s_mov_b32 m0, s40
	s_nop 0
	global_load_lds_dwordx4 v[216:217], off
	s_waitcnt vmcnt(8)
	s_waitcnt lgkmcnt(0)
	s_barrier
; #define PG8_STAGE(bufoff, gbase, voff) do { _Pragma("unroll") for (int _i = 0; _i < 2; ++_i) \
;         __builtin_amdgcn_global_load_lds((const unsigned*)((const char*)(gbase) + (voff)[_i]), (PG8_LAS unsigned*)(lds + (bufoff) + ldsw + _i * 8192), 16, 0, 0); } while (0)
; #define PG8_LDA(dst, b, h) do { _Pragma("unroll") for (int m = 0; m < 4; ++m) _Pragma("unroll") for (int k = 0; k < 2; ++k) dst[m][k] = *(const PG8_LAS bf16x8*)(lds + PG8_SA(b, h) + aoff + m * 2048 + k * 1024); } while (0)
; #define PG8_LDB(dst, b, h) do { _Pragma("unroll") for (int n = 0; n < 2; ++n) _Pragma("unroll") for (int k = 0; k < 2; ++k) dst[n][k] = *(const PG8_LAS bf16x8*)(lds + PG8_SB(b, h) + boff + n * 2048 + k * 1024); } while (0)
; #define PG8_MMA(ai, bj, At, Bt) do { __builtin_amdgcn_s_setprio(1); _Pragma("unroll") for (int m = 0; m < 4; ++m) _Pragma("unroll") for (int n = 0; n < 2; ++n) _Pragma("unroll") for (int k = 0; k < 2; ++k) \
;         acc[ai][bj][m][n] = __builtin_amdgcn_mfma_f32_16x16x32_bf16(Bt[n][k], At[m][k], acc[ai][bj][m][n], 0, 0, 0); __builtin_amdgcn_s_setprio(0); } while (0)
; #define PG8_WAIT_V(n) asm volatile("s_waitcnt vmcnt(" #n ")" ::: "memory")
; #define PG8_WAIT_L(n) asm volatile("s_waitcnt lgkmcnt(" #n ")" ::: "memory")
; #define PG8_BAR __builtin_amdgcn_s_barrier()
; #define PG8_SCHED __builtin_amdgcn_sched_barrier(0)
; template <class Epi, class Sched, bool ALIGN_EPI = false, bool SP2 = false>
; __device__ __forceinline__ void gemm_phase(PG8_LAS unsigned char* lds, const Gemm g, const Sched& S, const Epi& E, int wave_sgpr) {
;     ...
;             PG8_WAIT_V(8); PG8_WAIT_L(0); PG8_BAR; PG8_MMA(1, 0, At, B0); PG8_MMA(1, 1, At, B1); PG8_BAR; PG8_SCHED;
;             PG8_LDB(B0, 1, 0); PG8_LDB(B1, 1, 1); PG8_SCHED; PG8_LDA(At, 1, 0); PG8_STAGE(PG8_SA(0, 1), a2 + hstepA, voffA);
;             PG8_WAIT_V(8); PG8_WAIT_L(0); PG8_BAR; PG8_MMA(0, 0, At, B0); PG8_MMA(0, 1, At, B1); PG8_BAR; PG8_SCHED;
	s_setprio 1
	s_waitcnt lgkmcnt(0)
	v_mfma_f32_16x16x32_bf16 v[68:71], v[56:59], v[180:183], v[68:71]
	v_mfma_f32_16x16x32_bf16 v[64:67], v[72:75], v[180:183], v[64:67]
	v_mfma_f32_16x16x32_bf16 v[44:47], v[56:59], v[188:191], v[44:47]
	v_mfma_f32_16x16x32_bf16 v[40:43], v[72:75], v[188:191], v[40:43]
	v_mfma_f32_16x16x32_bf16 v[28:31], v[56:59], v[196:199], v[28:31]
	v_mfma_f32_16x16x32_bf16 v[24:27], v[72:75], v[196:199], v[24:27]
	v_mfma_f32_16x16x32_bf16 v[12:15], v[56:59], v[204:207], v[12:15]
	v_mfma_f32_16x16x32_bf16 v[8:11], v[72:75], v[204:207], v[8:11]
	v_mfma_f32_16x16x32_bf16 v[68:71], v[60:63], v[184:187], v[68:71]
	v_mfma_f32_16x16x32_bf16 v[64:67], v[76:79], v[184:187], v[64:67]
	v_mfma_f32_16x16x32_bf16 v[44:47], v[60:63], v[192:195], v[44:47]
	v_mfma_f32_16x16x32_bf16 v[40:43], v[76:79], v[192:195], v[40:43]
	v_mfma_f32_16x16x32_bf16 v[28:31], v[60:63], v[200:203], v[28:31]
	v_mfma_f32_16x16x32_bf16 v[24:27], v[76:79], v[200:203], v[24:27]
	v_mfma_f32_16x16x32_bf16 v[12:15], v[60:63], v[208:211], v[12:15]
	v_mfma_f32_16x16x32_bf16 v[8:11], v[76:79], v[208:211], v[8:11]
	v_mfma_f32_16x16x32_bf16 v[52:55], v[156:159], v[180:183], v[52:55]
	v_mfma_f32_16x16x32_bf16 v[48:51], v[172:175], v[180:183], v[48:51]
	v_mfma_f32_16x16x32_bf16 v[36:39], v[156:159], v[188:191], v[36:39]
	v_mfma_f32_16x16x32_bf16 v[32:35], v[172:175], v[188:191], v[32:35]
	v_mfma_f32_16x16x32_bf16 v[20:23], v[156:159], v[196:199], v[20:23]
	v_mfma_f32_16x16x32_bf16 v[16:19], v[172:175], v[196:199], v[16:19]
	v_mfma_f32_16x16x32_bf16 v[4:7], v[156:159], v[204:207], v[4:7]
	v_mfma_f32_16x16x32_bf16 v[0:3], v[172:175], v[204:207], v[0:3]
	v_mfma_f32_16x16x32_bf16 v[52:55], v[168:171], v[184:187], v[52:55]
	v_mfma_f32_16x16x32_bf16 v[48:51], v[176:179], v[184:187], v[48:51]
	v_mfma_f32_16x16x32_bf16 v[36:39], v[168:171], v[192:195], v[36:39]
	v_mfma_f32_16x16x32_bf16 v[32:35], v[176:179], v[192:195], v[32:35]
	v_mfma_f32_16x16x32_bf16 v[20:23], v[168:171], v[200:203], v[20:23]
	v_mfma_f32_16x16x32_bf16 v[16:19], v[176:179], v[200:203], v[16:19]
	v_mfma_f32_16x16x32_bf16 v[4:7], v[168:171], v[208:211], v[4:7]
	v_mfma_f32_16x16x32_bf16 v[0:3], v[176:179], v[208:211], v[0:3]
	s_setprio 0
	s_barrier
	s_add_i32 s62, 0, 0x18000
	s_add_i32 s63, 0, 0x1c000
	v_add_u32_e32 v76, s62, v164
	v_add_u32_e32 v176, s63, v164
	ds_read_b128 v[56:59], v76
	ds_read_b128 v[60:63], v76 offset:1024
	ds_read_b128 v[72:75], v76 offset:2048
	ds_read_b128 v[76:79], v76 offset:3072
	ds_read_b128 v[156:159], v176
	ds_read_b128 v[168:171], v176 offset:1024
	ds_read_b128 v[172:175], v176 offset:2048
	ds_read_b128 v[176:179], v176 offset:3072
	s_add_u32 s26, s26, 0x40000
	s_addc_u32 s27, s27, 0
	s_mov_b32 m0, s41
	v_lshl_add_u64 v[218:219], s[26:27], 0, v[150:151]
	ds_read_b128 v[180:183], v167 offset:32768
	ds_read_b128 v[184:187], v167 offset:33792
	ds_read_b128 v[188:191], v167 offset:34816
	ds_read_b128 v[192:195], v167 offset:35840
	ds_read_b128 v[196:199], v167 offset:36864
	ds_read_b128 v[200:203], v167 offset:37888
	ds_read_b128 v[204:207], v167 offset:38912
	ds_read_b128 v[208:211], v167 offset:39936
	global_load_lds_dwordx4 v[218:219], off
	v_lshl_add_u64 v[218:219], s[26:27], 0, v[146:147]
	s_mov_b32 m0, s42
	s_nop 0
	global_load_lds_dwordx4 v[218:219], off
	s_waitcnt vmcnt(8)
	s_waitcnt lgkmcnt(0)
	s_barrier
	s_setprio 1
	s_waitcnt lgkmcnt(0)
	v_mfma_f32_16x16x32_bf16 v[140:143], v[56:59], v[180:183], v[140:143]
	v_mfma_f32_16x16x32_bf16 v[136:139], v[72:75], v[180:183], v[136:139]
	v_mfma_f32_16x16x32_bf16 v[124:127], v[56:59], v[188:191], v[124:127]
	v_mfma_f32_16x16x32_bf16 v[120:123], v[72:75], v[188:191], v[120:123]
	v_mfma_f32_16x16x32_bf16 v[108:111], v[56:59], v[196:199], v[108:111]
	v_mfma_f32_16x16x32_bf16 v[104:107], v[72:75], v[196:199], v[104:107]
	v_mfma_f32_16x16x32_bf16 v[92:95], v[56:59], v[204:207], v[92:95]
	v_mfma_f32_16x16x32_bf16 v[88:91], v[72:75], v[204:207], v[88:91]
	v_mfma_f32_16x16x32_bf16 v[140:143], v[60:63], v[184:187], v[140:143]
	v_mfma_f32_16x16x32_bf16 v[136:139], v[76:79], v[184:187], v[136:139]
	v_mfma_f32_16x16x32_bf16 v[124:127], v[60:63], v[192:195], v[124:127]
	v_mfma_f32_16x16x32_bf16 v[120:123], v[76:79], v[192:195], v[120:123]
	v_mfma_f32_16x16x32_bf16 v[108:111], v[60:63], v[200:203], v[108:111]
	v_mfma_f32_16x16x32_bf16 v[104:107], v[76:79], v[200:203], v[104:107]
	v_mfma_f32_16x16x32_bf16 v[92:95], v[60:63], v[208:211], v[92:95]
	v_mfma_f32_16x16x32_bf16 v[88:91], v[76:79], v[208:211], v[88:91]
	v_mfma_f32_16x16x32_bf16 v[132:135], v[156:159], v[180:183], v[132:135]
	v_mfma_f32_16x16x32_bf16 v[128:131], v[172:175], v[180:183], v[128:131]
	v_mfma_f32_16x16x32_bf16 v[116:119], v[156:159], v[188:191], v[116:119]
	v_mfma_f32_16x16x32_bf16 v[112:115], v[172:175], v[188:191], v[112:115]
	v_mfma_f32_16x16x32_bf16 v[100:103], v[156:159], v[196:199], v[100:103]
	v_mfma_f32_16x16x32_bf16 v[96:99], v[172:175], v[196:199], v[96:99]
	v_mfma_f32_16x16x32_bf16 v[84:87], v[156:159], v[204:207], v[84:87]
	v_mfma_f32_16x16x32_bf16 v[80:83], v[172:175], v[204:207], v[80:83]
	v_mfma_f32_16x16x32_bf16 v[132:135], v[168:171], v[184:187], v[132:135]
	v_mfma_f32_16x16x32_bf16 v[128:131], v[176:179], v[184:187], v[128:131]
	v_mfma_f32_16x16x32_bf16 v[116:119], v[168:171], v[192:195], v[116:119]
	v_mfma_f32_16x16x32_bf16 v[112:115], v[176:179], v[192:195], v[112:115]
	v_mfma_f32_16x16x32_bf16 v[100:103], v[168:171], v[200:203], v[100:103]
	v_mfma_f32_16x16x32_bf16 v[96:99], v[176:179], v[200:203], v[96:99]
	v_mfma_f32_16x16x32_bf16 v[84:87], v[168:171], v[208:211], v[84:87]
	v_mfma_f32_16x16x32_bf16 v[80:83], v[176:179], v[208:211], v[80:83]
	s_setprio 0
	s_barrier
; #define PG8_STAGE(bufoff, gbase, voff) do { _Pragma("unroll") for (int _i = 0; _i < 2; ++_i) \
;         __builtin_amdgcn_global_load_lds((const unsigned*)((const char*)(gbase) + (voff)[_i]), (PG8_LAS unsigned*)(lds + (bufoff) + ldsw + _i * 8192), 16, 0, 0); } while (0)
; #define PG8_LDA(dst, b, h) do { _Pragma("unroll") for (int m = 0; m < 4; ++m) _Pragma("unroll") for (int k = 0; k < 2; ++k) dst[m][k] = *(const PG8_LAS bf16x8*)(lds + PG8_SA(b, h) + aoff + m * 2048 + k * 1024); } while (0)
; #define PG8_MMA(ai, bj, At, Bt) do { __builtin_amdgcn_s_setprio(1); _Pragma("unroll") for (int m = 0; m < 4; ++m) _Pragma("unroll") for (int n = 0; n < 2; ++n) _Pragma("unroll") for (int k = 0; k < 2; ++k) \
;         acc[ai][bj][m][n] = __builtin_amdgcn_mfma_f32_16x16x32_bf16(Bt[n][k], At[m][k], acc[ai][bj][m][n], 0, 0, 0); __builtin_amdgcn_s_setprio(0); } while (0)
; #define PG8_WAIT_V(n) asm volatile("s_waitcnt vmcnt(" #n ")" ::: "memory")
; #define PG8_WAIT_L(n) asm volatile("s_waitcnt lgkmcnt(" #n ")" ::: "memory")
; #define PG8_BAR __builtin_amdgcn_s_barrier()
; #define PG8_SCHED __builtin_amdgcn_sched_barrier(0)
; template <class Epi, class Sched, bool ALIGN_EPI = false, bool SP2 = false>
; __device__ __forceinline__ void gemm_phase(PG8_LAS unsigned char* lds, const Gemm g, const Sched& S, const Epi& E, int wave_sgpr) {
;     ...
;         for (int t = 0; t < nt; t += 2) {
;             const bool last = (t == nt - 2);
;             const char* a1 = cA + (size_t)(t + 1) * kstep;
;             const char* a2 = last ? nA : cA + (size_t)(t + 2) * kstep; const char* b2 = last ? nB : cB + (size_t)(t + 2) * kstep;
;     ...
;             PG8_LDA(At, 1, 1); PG8_STAGE(PG8_SB(1, 0), b3, voffB); PG8_STAGE(PG8_SB(1, 1), b3 + hstepB, voffB); PG8_STAGE(PG8_SA(1, 0), a3, voffA);
;             PG8_WAIT_V(8); PG8_WAIT_L(0); PG8_BAR; PG8_MMA(1, 0, At, B0); PG8_MMA(1, 1, At, B1); PG8_BAR; PG8_SCHED;
	s_add_i32 s26, s62, s29
	v_lshl_add_u64 v[160:161], v[160:161], 0, s[12:13]
	s_mov_b32 m0, s26
	ds_read_b128 v[180:183], v167 offset:49152
	ds_read_b128 v[184:187], v167 offset:50176
	ds_read_b128 v[188:191], v167 offset:51200
	ds_read_b128 v[192:195], v167 offset:52224
	ds_read_b128 v[196:199], v167 offset:53248
	ds_read_b128 v[200:203], v167 offset:54272
	ds_read_b128 v[204:207], v167 offset:55296
	ds_read_b128 v[208:211], v167 offset:56320
	global_load_lds_dwordx4 v[160:161], off
	s_add_i32 m0, s26, 0x2000
	s_add_u32 s24, s24, 0x80800
	v_lshl_add_u64 v[160:161], v[212:213], 0, s[12:13]
	s_addc_u32 s25, s25, 0
	s_add_i32 s26, s63, s29
	global_load_lds_dwordx4 v[160:161], off
	v_lshl_add_u64 v[160:161], s[24:25], 0, v[148:149]
	s_mov_b32 m0, s26
	s_nop 0
	global_load_lds_dwordx4 v[160:161], off
	v_lshl_add_u64 v[160:161], s[24:25], 0, v[144:145]
	s_add_i32 m0, s26, 0x2000
	s_nop 0
	global_load_lds_dwordx4 v[160:161], off
	v_lshl_add_u64 v[160:161], v[214:215], 0, s[12:13]
	s_mov_b32 m0, s45
	s_nop 0
	global_load_lds_dwordx4 v[160:161], off
	v_lshl_add_u64 v[160:161], v[216:217], 0, s[12:13]
	s_mov_b32 m0, s46
	s_nop 0
	global_load_lds_dwordx4 v[160:161], off
	s_waitcnt vmcnt(8)
	s_waitcnt lgkmcnt(0)
	s_barrier
	s_setprio 1
	s_waitcnt lgkmcnt(0)
	v_mfma_f32_16x16x32_bf16 v[68:71], v[56:59], v[180:183], v[68:71]
	v_mfma_f32_16x16x32_bf16 v[64:67], v[72:75], v[180:183], v[64:67]
	v_mfma_f32_16x16x32_bf16 v[44:47], v[56:59], v[188:191], v[44:47]
	v_mfma_f32_16x16x32_bf16 v[40:43], v[72:75], v[188:191], v[40:43]
	v_mfma_f32_16x16x32_bf16 v[28:31], v[56:59], v[196:199], v[28:31]
	v_mfma_f32_16x16x32_bf16 v[24:27], v[72:75], v[196:199], v[24:27]
	v_mfma_f32_16x16x32_bf16 v[12:15], v[56:59], v[204:207], v[12:15]
	v_mfma_f32_16x16x32_bf16 v[8:11], v[72:75], v[204:207], v[8:11]
	v_mfma_f32_16x16x32_bf16 v[68:71], v[60:63], v[184:187], v[68:71]
	v_mfma_f32_16x16x32_bf16 v[64:67], v[76:79], v[184:187], v[64:67]
	v_mfma_f32_16x16x32_bf16 v[44:47], v[60:63], v[192:195], v[44:47]
	v_mfma_f32_16x16x32_bf16 v[40:43], v[76:79], v[192:195], v[40:43]
	v_mfma_f32_16x16x32_bf16 v[28:31], v[60:63], v[200:203], v[28:31]
	v_mfma_f32_16x16x32_bf16 v[24:27], v[76:79], v[200:203], v[24:27]
	v_mfma_f32_16x16x32_bf16 v[12:15], v[60:63], v[208:211], v[12:15]
	v_mfma_f32_16x16x32_bf16 v[8:11], v[76:79], v[208:211], v[8:11]
	v_mfma_f32_16x16x32_bf16 v[52:55], v[156:159], v[180:183], v[52:55]
	v_mfma_f32_16x16x32_bf16 v[48:51], v[172:175], v[180:183], v[48:51]
	v_mfma_f32_16x16x32_bf16 v[36:39], v[156:159], v[188:191], v[36:39]
	v_mfma_f32_16x16x32_bf16 v[32:35], v[172:175], v[188:191], v[32:35]
	v_mfma_f32_16x16x32_bf16 v[20:23], v[156:159], v[196:199], v[20:23]
	v_mfma_f32_16x16x32_bf16 v[16:19], v[172:175], v[196:199], v[16:19]
	v_mfma_f32_16x16x32_bf16 v[4:7], v[156:159], v[204:207], v[4:7]
	v_mfma_f32_16x16x32_bf16 v[0:3], v[172:175], v[204:207], v[0:3]
	v_mfma_f32_16x16x32_bf16 v[52:55], v[168:171], v[184:187], v[52:55]
	v_mfma_f32_16x16x32_bf16 v[48:51], v[176:179], v[184:187], v[48:51]
	v_mfma_f32_16x16x32_bf16 v[36:39], v[168:171], v[192:195], v[36:39]
	v_mfma_f32_16x16x32_bf16 v[32:35], v[176:179], v[192:195], v[32:35]
	v_mfma_f32_16x16x32_bf16 v[20:23], v[168:171], v[200:203], v[20:23]
	v_mfma_f32_16x16x32_bf16 v[16:19], v[176:179], v[200:203], v[16:19]
	v_mfma_f32_16x16x32_bf16 v[4:7], v[168:171], v[208:211], v[4:7]
	v_mfma_f32_16x16x32_bf16 v[0:3], v[176:179], v[208:211], v[0:3]
	s_setprio 0
	s_barrier
	s_add_i32 s61, s61, 2
	s_add_u32 s22, s22, 0x80
	s_addc_u32 s23, s23, 0
	s_add_u32 s59, s59, 0x80
	s_addc_u32 s60, s60, 0
	s_cmp_gt_u32 s61, 29
	s_cbranch_scc0 .LBB0_1077
	s_and_b64 vcc, exec, s[14:15]
	s_cbranch_vccz .LBB0_1080
	s_barrier

; #define PG8_STAGE(bufoff, gbase, voff) do { _Pragma("unroll") for (int _i = 0; _i < 2; ++_i) \
;         __builtin_amdgcn_global_load_lds((const unsigned*)((const char*)(gbase) + (voff)[_i]), (PG8_LAS unsigned*)(lds + (bufoff) + ldsw + _i * 8192), 16, 0, 0); } while (0)
; #define PG8_LDA(dst, b, h) do { _Pragma("unroll") for (int m = 0; m < 4; ++m) _Pragma("unroll") for (int k = 0; k < 2; ++k) dst[m][k] = *(const PG8_LAS bf16x8*)(lds + PG8_SA(b, h) + aoff + m * 2048 + k * 1024); } while (0)
; #define PG8_LDB(dst, b, h) do { _Pragma("unroll") for (int n = 0; n < 2; ++n) _Pragma("unroll") for (int k = 0; k < 2; ++k) dst[n][k] = *(const PG8_LAS bf16x8*)(lds + PG8_SB(b, h) + boff + n * 2048 + k * 1024); } while (0)
; #define PG8_MMA(ai, bj, At, Bt) do { __builtin_amdgcn_s_setprio(1); _Pragma("unroll") for (int m = 0; m < 4; ++m) _Pragma("unroll") for (int n = 0; n < 2; ++n) _Pragma("unroll") for (int k = 0; k < 2; ++k) \
;         acc[ai][bj][m][n] = __builtin_amdgcn_mfma_f32_16x16x32_bf16(Bt[n][k], At[m][k], acc[ai][bj][m][n], 0, 0, 0); __builtin_amdgcn_s_setprio(0); } while (0)
; #define PG8_WAIT_V(n) asm volatile("s_waitcnt vmcnt(" #n ")" ::: "memory")
; #define PG8_WAIT_L(n) asm volatile("s_waitcnt lgkmcnt(" #n ")" ::: "memory")
; #define PG8_BAR __builtin_amdgcn_s_barrier()
; #define PG8_SCHED __builtin_amdgcn_sched_barrier(0)
; template <class Epi, class Sched, bool ALIGN_EPI = false, bool SP2 = false>
; __device__ __forceinline__ void gemm_phase(PG8_LAS unsigned char* lds, const Gemm g, const Sched& S, const Epi& E, int wave_sgpr) {
;     ...
;             PG8_LDB(B0, 0, 0); PG8_LDB(B1, 0, 1); PG8_SCHED; PG8_LDA(At, 0, 0); PG8_STAGE(PG8_SA(1, 1), a1 + hstepA, voffA);
;             PG8_WAIT_V(8); PG8_WAIT_L(0); PG8_BAR; PG8_MMA(0, 0, At, B0); PG8_MMA(0, 1, At, B1); PG8_BAR; PG8_SCHED;
;             PG8_LDA(At, 0, 1); PG8_STAGE(PG8_SB(0, 0), b2, voffB); PG8_STAGE(PG8_SB(0, 1), b2 + hstepB, voffB); PG8_STAGE(PG8_SA(0, 0), a2, voffA);
.LBB0_1103:
	ds_read_b128 v[56:59], v165
	ds_read_b128 v[60:63], v165 offset:1024
	ds_read_b128 v[72:75], v165 offset:2048
	ds_read_b128 v[76:79], v165 offset:3072
	ds_read_b128 v[156:159], v166
	ds_read_b128 v[168:171], v166 offset:1024
	ds_read_b128 v[172:175], v166 offset:2048
	ds_read_b128 v[176:179], v166 offset:3072
	s_add_u32 s26, s24, 0xfffc0080
	s_addc_u32 s27, s25, -1
	s_cmp_eq_u32 s63, 28
	s_cselect_b32 s29, s21, s27
	s_cselect_b32 s28, s20, s26
	s_cselect_b32 s27, s59, s62
	s_cselect_b32 s26, s60, s61
	s_mov_b32 m0, s49
	v_lshl_add_u64 v[160:161], s[24:25], 0, v[152:153]
	ds_read_b128 v[180:183], v167
	ds_read_b128 v[184:187], v167 offset:1024
	ds_read_b128 v[188:191], v167 offset:2048
	ds_read_b128 v[192:195], v167 offset:3072
	ds_read_b128 v[196:199], v167 offset:4096
	ds_read_b128 v[200:203], v167 offset:5120
	ds_read_b128 v[204:207], v167 offset:6144
	ds_read_b128 v[208:211], v167 offset:7168
	global_load_lds_dwordx4 v[160:161], off
	v_lshl_add_u64 v[160:161], s[24:25], 0, v[154:155]
	s_mov_b32 m0, s50
	s_nop 0
	global_load_lds_dwordx4 v[160:161], off
	s_waitcnt vmcnt(8)
	s_waitcnt lgkmcnt(0)
	s_barrier
	s_setprio 1
	s_waitcnt lgkmcnt(0)
	v_mfma_f32_16x16x32_bf16 v[140:143], v[56:59], v[180:183], v[140:143]
	v_mfma_f32_16x16x32_bf16 v[136:139], v[72:75], v[180:183], v[136:139]
	v_mfma_f32_16x16x32_bf16 v[124:127], v[56:59], v[188:191], v[124:127]
	v_mfma_f32_16x16x32_bf16 v[120:123], v[72:75], v[188:191], v[120:123]
	v_mfma_f32_16x16x32_bf16 v[108:111], v[56:59], v[196:199], v[108:111]
	v_mfma_f32_16x16x32_bf16 v[104:107], v[72:75], v[196:199], v[104:107]
	v_mfma_f32_16x16x32_bf16 v[92:95], v[56:59], v[204:207], v[92:95]
	v_mfma_f32_16x16x32_bf16 v[88:91], v[72:75], v[204:207], v[88:91]
	v_mfma_f32_16x16x32_bf16 v[140:143], v[60:63], v[184:187], v[140:143]
	v_mfma_f32_16x16x32_bf16 v[136:139], v[76:79], v[184:187], v[136:139]
	v_mfma_f32_16x16x32_bf16 v[124:127], v[60:63], v[192:195], v[124:127]
	v_mfma_f32_16x16x32_bf16 v[120:123], v[76:79], v[192:195], v[120:123]
	v_mfma_f32_16x16x32_bf16 v[108:111], v[60:63], v[200:203], v[108:111]
	v_mfma_f32_16x16x32_bf16 v[104:107], v[76:79], v[200:203], v[104:107]
	v_mfma_f32_16x16x32_bf16 v[92:95], v[60:63], v[208:211], v[92:95]
	v_mfma_f32_16x16x32_bf16 v[88:91], v[76:79], v[208:211], v[88:91]
	v_mfma_f32_16x16x32_bf16 v[132:135], v[156:159], v[180:183], v[132:135]
	v_mfma_f32_16x16x32_bf16 v[128:131], v[172:175], v[180:183], v[128:131]
	v_mfma_f32_16x16x32_bf16 v[116:119], v[156:159], v[188:191], v[116:119]
	v_mfma_f32_16x16x32_bf16 v[112:115], v[172:175], v[188:191], v[112:115]
	v_mfma_f32_16x16x32_bf16 v[100:103], v[156:159], v[196:199], v[100:103]
	v_mfma_f32_16x16x32_bf16 v[96:99], v[172:175], v[196:199], v[96:99]
	v_mfma_f32_16x16x32_bf16 v[84:87], v[156:159], v[204:207], v[84:87]
	v_mfma_f32_16x16x32_bf16 v[80:83], v[172:175], v[204:207], v[80:83]
	v_mfma_f32_16x16x32_bf16 v[132:135], v[168:171], v[184:187], v[132:135]
	v_mfma_f32_16x16x32_bf16 v[128:131], v[176:179], v[184:187], v[128:131]
	v_mfma_f32_16x16x32_bf16 v[116:119], v[168:171], v[192:195], v[116:119]
	v_mfma_f32_16x16x32_bf16 v[112:115], v[176:179], v[192:195], v[112:115]
	v_mfma_f32_16x16x32_bf16 v[100:103], v[168:171], v[200:203], v[100:103]
	v_mfma_f32_16x16x32_bf16 v[96:99], v[176:179], v[200:203], v[96:99]
	v_mfma_f32_16x16x32_bf16 v[84:87], v[168:171], v[208:211], v[84:87]
	v_mfma_f32_16x16x32_bf16 v[80:83], v[176:179], v[208:211], v[80:83]
	s_setprio 0
	s_barrier
	s_mov_b32 m0, s51
	v_lshl_add_u64 v[160:161], s[26:27], 0, v[148:149]
	s_add_u32 s64, s26, 0x80000
	ds_read_b128 v[180:183], v167 offset:16384
	ds_read_b128 v[184:187], v167 offset:17408
	ds_read_b128 v[188:191], v167 offset:18432
	ds_read_b128 v[192:195], v167 offset:19456
	ds_read_b128 v[196:199], v167 offset:20480
	ds_read_b128 v[200:203], v167 offset:21504
	ds_read_b128 v[204:207], v167 offset:22528
	ds_read_b128 v[208:211], v167 offset:23552
	global_load_lds_dwordx4 v[160:161], off
	v_lshl_add_u64 v[212:213], s[26:27], 0, v[144:145]
	s_mov_b32 m0, s52
	s_addc_u32 s65, s27, 0
	global_load_lds_dwordx4 v[212:213], off
	v_lshl_add_u64 v[214:215], s[64:65], 0, v[148:149]
	s_mov_b32 m0, s53
	v_lshl_add_u64 v[216:217], s[28:29], 0, v[146:147]
	global_load_lds_dwordx4 v[214:215], off
	v_lshl_add_u64 v[214:215], s[64:65], 0, v[144:145]
	s_mov_b32 m0, s54
	s_nop 0
	global_load_lds_dwordx4 v[214:215], off
	v_lshl_add_u64 v[214:215], s[28:29], 0, v[150:151]
	s_mov_b32 m0, s7
	s_nop 0
	global_load_lds_dwordx4 v[214:215], off
	s_mov_b32 m0, s42
	s_nop 0
	global_load_lds_dwordx4 v[216:217], off
	s_waitcnt vmcnt(8)
	s_waitcnt lgkmcnt(0)
	s_barrier
; #define PG8_STAGE(bufoff, gbase, voff) do { _Pragma("unroll") for (int _i = 0; _i < 2; ++_i) \
;         __builtin_amdgcn_global_load_lds((const unsigned*)((const char*)(gbase) + (voff)[_i]), (PG8_LAS unsigned*)(lds + (bufoff) + ldsw + _i * 8192), 16, 0, 0); } while (0)
; #define PG8_LDA(dst, b, h) do { _Pragma("unroll") for (int m = 0; m < 4; ++m) _Pragma("unroll") for (int k = 0; k < 2; ++k) dst[m][k] = *(const PG8_LAS bf16x8*)(lds + PG8_SA(b, h) + aoff + m * 2048 + k * 1024); } while (0)
; #define PG8_LDB(dst, b, h) do { _Pragma("unroll") for (int n = 0; n < 2; ++n) _Pragma("unroll") for (int k = 0; k < 2; ++k) dst[n][k] = *(const PG8_LAS bf16x8*)(lds + PG8_SB(b, h) + boff + n * 2048 + k * 1024); } while (0)
; #define PG8_MMA(ai, bj, At, Bt) do { __builtin_amdgcn_s_setprio(1); _Pragma("unroll") for (int m = 0; m < 4; ++m) _Pragma("unroll") for (int n = 0; n < 2; ++n) _Pragma("unroll") for (int k = 0; k < 2; ++k) \
;         acc[ai][bj][m][n] = __builtin_amdgcn_mfma_f32_16x16x32_bf16(Bt[n][k], At[m][k], acc[ai][bj][m][n], 0, 0, 0); __builtin_amdgcn_s_setprio(0); } while (0)
; #define PG8_WAIT_V(n) asm volatile("s_waitcnt vmcnt(" #n ")" ::: "memory")
; #define PG8_WAIT_L(n) asm volatile("s_waitcnt lgkmcnt(" #n ")" ::: "memory")
; #define PG8_BAR __builtin_amdgcn_s_barrier()
; #define PG8_SCHED __builtin_amdgcn_sched_barrier(0)
; template <class Epi, class Sched, bool ALIGN_EPI = false, bool SP2 = false>
; __device__ __forceinline__ void gemm_phase(PG8_LAS unsigned char* lds, const Gemm g, const Sched& S, const Epi& E, int wave_sgpr) {
;     ...
;             PG8_WAIT_V(8); PG8_WAIT_L(0); PG8_BAR; PG8_MMA(1, 0, At, B0); PG8_MMA(1, 1, At, B1); PG8_BAR; PG8_SCHED;
;             PG8_LDB(B0, 1, 0); PG8_LDB(B1, 1, 1); PG8_SCHED; PG8_LDA(At, 1, 0); PG8_STAGE(PG8_SA(0, 1), a2 + hstepA, voffA);
;             PG8_WAIT_V(8); PG8_WAIT_L(0); PG8_BAR; PG8_MMA(0, 0, At, B0); PG8_MMA(0, 1, At, B1); PG8_BAR; PG8_SCHED;
	s_setprio 1
	s_waitcnt lgkmcnt(0)
	v_mfma_f32_16x16x32_bf16 v[68:71], v[56:59], v[180:183], v[68:71]
	v_mfma_f32_16x16x32_bf16 v[64:67], v[72:75], v[180:183], v[64:67]
	v_mfma_f32_16x16x32_bf16 v[44:47], v[56:59], v[188:191], v[44:47]
	v_mfma_f32_16x16x32_bf16 v[40:43], v[72:75], v[188:191], v[40:43]
	v_mfma_f32_16x16x32_bf16 v[28:31], v[56:59], v[196:199], v[28:31]
	v_mfma_f32_16x16x32_bf16 v[24:27], v[72:75], v[196:199], v[24:27]
	v_mfma_f32_16x16x32_bf16 v[12:15], v[56:59], v[204:207], v[12:15]
	v_mfma_f32_16x16x32_bf16 v[8:11], v[72:75], v[204:207], v[8:11]
	v_mfma_f32_16x16x32_bf16 v[68:71], v[60:63], v[184:187], v[68:71]
	v_mfma_f32_16x16x32_bf16 v[64:67], v[76:79], v[184:187], v[64:67]
	v_mfma_f32_16x16x32_bf16 v[44:47], v[60:63], v[192:195], v[44:47]
	v_mfma_f32_16x16x32_bf16 v[40:43], v[76:79], v[192:195], v[40:43]
	v_mfma_f32_16x16x32_bf16 v[28:31], v[60:63], v[200:203], v[28:31]
	v_mfma_f32_16x16x32_bf16 v[24:27], v[76:79], v[200:203], v[24:27]
	v_mfma_f32_16x16x32_bf16 v[12:15], v[60:63], v[208:211], v[12:15]
	v_mfma_f32_16x16x32_bf16 v[8:11], v[76:79], v[208:211], v[8:11]
	v_mfma_f32_16x16x32_bf16 v[52:55], v[156:159], v[180:183], v[52:55]
	v_mfma_f32_16x16x32_bf16 v[48:51], v[172:175], v[180:183], v[48:51]
	v_mfma_f32_16x16x32_bf16 v[36:39], v[156:159], v[188:191], v[36:39]
	v_mfma_f32_16x16x32_bf16 v[32:35], v[172:175], v[188:191], v[32:35]
	v_mfma_f32_16x16x32_bf16 v[20:23], v[156:159], v[196:199], v[20:23]
	v_mfma_f32_16x16x32_bf16 v[16:19], v[172:175], v[196:199], v[16:19]
	v_mfma_f32_16x16x32_bf16 v[4:7], v[156:159], v[204:207], v[4:7]
	v_mfma_f32_16x16x32_bf16 v[0:3], v[172:175], v[204:207], v[0:3]
	v_mfma_f32_16x16x32_bf16 v[52:55], v[168:171], v[184:187], v[52:55]
	v_mfma_f32_16x16x32_bf16 v[48:51], v[176:179], v[184:187], v[48:51]
	v_mfma_f32_16x16x32_bf16 v[36:39], v[168:171], v[192:195], v[36:39]
	v_mfma_f32_16x16x32_bf16 v[32:35], v[176:179], v[192:195], v[32:35]
	v_mfma_f32_16x16x32_bf16 v[20:23], v[168:171], v[200:203], v[20:23]
	v_mfma_f32_16x16x32_bf16 v[16:19], v[176:179], v[200:203], v[16:19]
	v_mfma_f32_16x16x32_bf16 v[4:7], v[168:171], v[208:211], v[4:7]
	v_mfma_f32_16x16x32_bf16 v[0:3], v[176:179], v[208:211], v[0:3]
	s_setprio 0
	s_barrier
	s_add_i32 s64, 0, 0x18000
	s_add_i32 s65, 0, 0x1c000
	v_add_u32_e32 v76, s64, v164
	v_add_u32_e32 v176, s65, v164
	ds_read_b128 v[56:59], v76
	ds_read_b128 v[60:63], v76 offset:1024
	ds_read_b128 v[72:75], v76 offset:2048
	ds_read_b128 v[76:79], v76 offset:3072
	ds_read_b128 v[156:159], v176
	ds_read_b128 v[168:171], v176 offset:1024
	ds_read_b128 v[172:175], v176 offset:2048
	ds_read_b128 v[176:179], v176 offset:3072
	s_add_u32 s28, s28, 0x40000
	s_addc_u32 s29, s29, 0
	s_mov_b32 m0, s43
	v_lshl_add_u64 v[218:219], s[28:29], 0, v[150:151]
	ds_read_b128 v[180:183], v167 offset:32768
	ds_read_b128 v[184:187], v167 offset:33792
	ds_read_b128 v[188:191], v167 offset:34816
	ds_read_b128 v[192:195], v167 offset:35840
	ds_read_b128 v[196:199], v167 offset:36864
	ds_read_b128 v[200:203], v167 offset:37888
	ds_read_b128 v[204:207], v167 offset:38912
	ds_read_b128 v[208:211], v167 offset:39936
	global_load_lds_dwordx4 v[218:219], off
	v_lshl_add_u64 v[218:219], s[28:29], 0, v[146:147]
	s_mov_b32 m0, s44
	s_nop 0
	global_load_lds_dwordx4 v[218:219], off
	s_waitcnt vmcnt(8)
	s_waitcnt lgkmcnt(0)
	s_barrier
	s_setprio 1
	s_waitcnt lgkmcnt(0)
	v_mfma_f32_16x16x32_bf16 v[140:143], v[56:59], v[180:183], v[140:143]
	v_mfma_f32_16x16x32_bf16 v[136:139], v[72:75], v[180:183], v[136:139]
	v_mfma_f32_16x16x32_bf16 v[124:127], v[56:59], v[188:191], v[124:127]
	v_mfma_f32_16x16x32_bf16 v[120:123], v[72:75], v[188:191], v[120:123]
	v_mfma_f32_16x16x32_bf16 v[108:111], v[56:59], v[196:199], v[108:111]
	v_mfma_f32_16x16x32_bf16 v[104:107], v[72:75], v[196:199], v[104:107]
	v_mfma_f32_16x16x32_bf16 v[92:95], v[56:59], v[204:207], v[92:95]
	v_mfma_f32_16x16x32_bf16 v[88:91], v[72:75], v[204:207], v[88:91]
	v_mfma_f32_16x16x32_bf16 v[140:143], v[60:63], v[184:187], v[140:143]
	v_mfma_f32_16x16x32_bf16 v[136:139], v[76:79], v[184:187], v[136:139]
	v_mfma_f32_16x16x32_bf16 v[124:127], v[60:63], v[192:195], v[124:127]
	v_mfma_f32_16x16x32_bf16 v[120:123], v[76:79], v[192:195], v[120:123]
	v_mfma_f32_16x16x32_bf16 v[108:111], v[60:63], v[200:203], v[108:111]
	v_mfma_f32_16x16x32_bf16 v[104:107], v[76:79], v[200:203], v[104:107]
	v_mfma_f32_16x16x32_bf16 v[92:95], v[60:63], v[208:211], v[92:95]
	v_mfma_f32_16x16x32_bf16 v[88:91], v[76:79], v[208:211], v[88:91]
	v_mfma_f32_16x16x32_bf16 v[132:135], v[156:159], v[180:183], v[132:135]
	v_mfma_f32_16x16x32_bf16 v[128:131], v[172:175], v[180:183], v[128:131]
	v_mfma_f32_16x16x32_bf16 v[116:119], v[156:159], v[188:191], v[116:119]
	v_mfma_f32_16x16x32_bf16 v[112:115], v[172:175], v[188:191], v[112:115]
	v_mfma_f32_16x16x32_bf16 v[100:103], v[156:159], v[196:199], v[100:103]
	v_mfma_f32_16x16x32_bf16 v[96:99], v[172:175], v[196:199], v[96:99]
	v_mfma_f32_16x16x32_bf16 v[84:87], v[156:159], v[204:207], v[84:87]
	v_mfma_f32_16x16x32_bf16 v[80:83], v[172:175], v[204:207], v[80:83]
	v_mfma_f32_16x16x32_bf16 v[132:135], v[168:171], v[184:187], v[132:135]
	v_mfma_f32_16x16x32_bf16 v[128:131], v[176:179], v[184:187], v[128:131]
	v_mfma_f32_16x16x32_bf16 v[116:119], v[168:171], v[192:195], v[116:119]
	v_mfma_f32_16x16x32_bf16 v[112:115], v[176:179], v[192:195], v[112:115]
	v_mfma_f32_16x16x32_bf16 v[100:103], v[168:171], v[200:203], v[100:103]
	v_mfma_f32_16x16x32_bf16 v[96:99], v[176:179], v[200:203], v[96:99]
	v_mfma_f32_16x16x32_bf16 v[84:87], v[168:171], v[208:211], v[84:87]
	v_mfma_f32_16x16x32_bf16 v[80:83], v[176:179], v[208:211], v[80:83]
	s_setprio 0
	s_barrier
; #define PG8_STAGE(bufoff, gbase, voff) do { _Pragma("unroll") for (int _i = 0; _i < 2; ++_i) \
;         __builtin_amdgcn_global_load_lds((const unsigned*)((const char*)(gbase) + (voff)[_i]), (PG8_LAS unsigned*)(lds + (bufoff) + ldsw + _i * 8192), 16, 0, 0); } while (0)
; #define PG8_LDA(dst, b, h) do { _Pragma("unroll") for (int m = 0; m < 4; ++m) _Pragma("unroll") for (int k = 0; k < 2; ++k) dst[m][k] = *(const PG8_LAS bf16x8*)(lds + PG8_SA(b, h) + aoff + m * 2048 + k * 1024); } while (0)
; #define PG8_MMA(ai, bj, At, Bt) do { __builtin_amdgcn_s_setprio(1); _Pragma("unroll") for (int m = 0; m < 4; ++m) _Pragma("unroll") for (int n = 0; n < 2; ++n) _Pragma("unroll") for (int k = 0; k < 2; ++k) \
;         acc[ai][bj][m][n] = __builtin_amdgcn_mfma_f32_16x16x32_bf16(Bt[n][k], At[m][k], acc[ai][bj][m][n], 0, 0, 0); __builtin_amdgcn_s_setprio(0); } while (0)
; #define PG8_WAIT_V(n) asm volatile("s_waitcnt vmcnt(" #n ")" ::: "memory")
; #define PG8_WAIT_L(n) asm volatile("s_waitcnt lgkmcnt(" #n ")" ::: "memory")
; #define PG8_BAR __builtin_amdgcn_s_barrier()
; #define PG8_SCHED __builtin_amdgcn_sched_barrier(0)
; template <class Epi, class Sched, bool ALIGN_EPI = false, bool SP2 = false>
; __device__ __forceinline__ void gemm_phase(PG8_LAS unsigned char* lds, const Gemm g, const Sched& S, const Epi& E, int wave_sgpr) {
;     ...
;         for (int t = 0; t < nt; t += 2) {
;             const bool last = (t == nt - 2);
;             const char* a1 = cA + (size_t)(t + 1) * kstep;
;             const char* a2 = last ? nA : cA + (size_t)(t + 2) * kstep; const char* b2 = last ? nB : cB + (size_t)(t + 2) * kstep;
;     ...
;             PG8_LDA(At, 1, 1); PG8_STAGE(PG8_SB(1, 0), b3, voffB); PG8_STAGE(PG8_SB(1, 1), b3 + hstepB, voffB); PG8_STAGE(PG8_SA(1, 0), a3, voffA);
;             PG8_WAIT_V(8); PG8_WAIT_L(0); PG8_BAR; PG8_MMA(1, 0, At, B0); PG8_MMA(1, 1, At, B1); PG8_BAR; PG8_SCHED;
	s_add_i32 s28, s64, s41
	v_lshl_add_u64 v[160:161], v[160:161], 0, s[14:15]
	s_mov_b32 m0, s28
	ds_read_b128 v[180:183], v167 offset:49152
	ds_read_b128 v[184:187], v167 offset:50176
	ds_read_b128 v[188:191], v167 offset:51200
	ds_read_b128 v[192:195], v167 offset:52224
	ds_read_b128 v[196:199], v167 offset:53248
	ds_read_b128 v[200:203], v167 offset:54272
	ds_read_b128 v[204:207], v167 offset:55296
	ds_read_b128 v[208:211], v167 offset:56320
	global_load_lds_dwordx4 v[160:161], off
	s_add_i32 m0, s28, 0x2000
	s_add_u32 s26, s26, 0x80080
	v_lshl_add_u64 v[160:161], v[212:213], 0, s[14:15]
	s_addc_u32 s27, s27, 0
	s_add_i32 s28, s65, s41
	global_load_lds_dwordx4 v[160:161], off
	v_lshl_add_u64 v[160:161], s[26:27], 0, v[148:149]
	s_mov_b32 m0, s28
	s_nop 0
	global_load_lds_dwordx4 v[160:161], off
	v_lshl_add_u64 v[160:161], s[26:27], 0, v[144:145]
	s_add_i32 m0, s28, 0x2000
	s_nop 0
	global_load_lds_dwordx4 v[160:161], off
	v_lshl_add_u64 v[160:161], v[214:215], 0, s[14:15]
	s_mov_b32 m0, s47
	s_nop 0
	global_load_lds_dwordx4 v[160:161], off
	v_lshl_add_u64 v[160:161], v[216:217], 0, s[14:15]
	s_mov_b32 m0, s48
	s_nop 0
	global_load_lds_dwordx4 v[160:161], off
	s_waitcnt vmcnt(8)
	s_waitcnt lgkmcnt(0)
	s_barrier
	s_setprio 1
	s_waitcnt lgkmcnt(0)
	v_mfma_f32_16x16x32_bf16 v[68:71], v[56:59], v[180:183], v[68:71]
	v_mfma_f32_16x16x32_bf16 v[64:67], v[72:75], v[180:183], v[64:67]
	v_mfma_f32_16x16x32_bf16 v[44:47], v[56:59], v[188:191], v[44:47]
	v_mfma_f32_16x16x32_bf16 v[40:43], v[72:75], v[188:191], v[40:43]
	v_mfma_f32_16x16x32_bf16 v[28:31], v[56:59], v[196:199], v[28:31]
	v_mfma_f32_16x16x32_bf16 v[24:27], v[72:75], v[196:199], v[24:27]
	v_mfma_f32_16x16x32_bf16 v[12:15], v[56:59], v[204:207], v[12:15]
	v_mfma_f32_16x16x32_bf16 v[8:11], v[72:75], v[204:207], v[8:11]
	v_mfma_f32_16x16x32_bf16 v[68:71], v[60:63], v[184:187], v[68:71]
	v_mfma_f32_16x16x32_bf16 v[64:67], v[76:79], v[184:187], v[64:67]
	v_mfma_f32_16x16x32_bf16 v[44:47], v[60:63], v[192:195], v[44:47]
	v_mfma_f32_16x16x32_bf16 v[40:43], v[76:79], v[192:195], v[40:43]
	v_mfma_f32_16x16x32_bf16 v[28:31], v[60:63], v[200:203], v[28:31]
	v_mfma_f32_16x16x32_bf16 v[24:27], v[76:79], v[200:203], v[24:27]
	v_mfma_f32_16x16x32_bf16 v[12:15], v[60:63], v[208:211], v[12:15]
	v_mfma_f32_16x16x32_bf16 v[8:11], v[76:79], v[208:211], v[8:11]
	v_mfma_f32_16x16x32_bf16 v[52:55], v[156:159], v[180:183], v[52:55]
	v_mfma_f32_16x16x32_bf16 v[48:51], v[172:175], v[180:183], v[48:51]
	v_mfma_f32_16x16x32_bf16 v[36:39], v[156:159], v[188:191], v[36:39]
	v_mfma_f32_16x16x32_bf16 v[32:35], v[172:175], v[188:191], v[32:35]
	v_mfma_f32_16x16x32_bf16 v[20:23], v[156:159], v[196:199], v[20:23]
	v_mfma_f32_16x16x32_bf16 v[16:19], v[172:175], v[196:199], v[16:19]
	v_mfma_f32_16x16x32_bf16 v[4:7], v[156:159], v[204:207], v[4:7]
	v_mfma_f32_16x16x32_bf16 v[0:3], v[172:175], v[204:207], v[0:3]
	v_mfma_f32_16x16x32_bf16 v[52:55], v[168:171], v[184:187], v[52:55]
	v_mfma_f32_16x16x32_bf16 v[48:51], v[176:179], v[184:187], v[48:51]
	v_mfma_f32_16x16x32_bf16 v[36:39], v[168:171], v[192:195], v[36:39]
	v_mfma_f32_16x16x32_bf16 v[32:35], v[176:179], v[192:195], v[32:35]
	v_mfma_f32_16x16x32_bf16 v[20:23], v[168:171], v[200:203], v[20:23]
	v_mfma_f32_16x16x32_bf16 v[16:19], v[176:179], v[200:203], v[16:19]
	v_mfma_f32_16x16x32_bf16 v[4:7], v[168:171], v[208:211], v[4:7]
	v_mfma_f32_16x16x32_bf16 v[0:3], v[176:179], v[208:211], v[0:3]
	s_setprio 0
	s_barrier
	s_add_i32 s63, s63, 2
	s_add_u32 s24, s24, 0x100
	s_addc_u32 s25, s25, 0
	s_add_u32 s61, s61, 0x100
	s_addc_u32 s62, s62, 0
	s_cmp_gt_u32 s63, 29
	s_cbranch_scc0 .LBB0_1103
	s_and_b64 vcc, exec, s[16:17]
	s_cbranch_vccz .LBB0_1106
	s_barrier

; #define PG8_STAGE(bufoff, gbase, voff) do { _Pragma("unroll") for (int _i = 0; _i < 2; ++_i) \
;         __builtin_amdgcn_global_load_lds((const unsigned*)((const char*)(gbase) + (voff)[_i]), (PG8_LAS unsigned*)(lds + (bufoff) + ldsw + _i * 8192), 16, 0, 0); } while (0)
; #define PG8_LDA(dst, b, h) do { _Pragma("unroll") for (int m = 0; m < 4; ++m) _Pragma("unroll") for (int k = 0; k < 2; ++k) dst[m][k] = *(const PG8_LAS bf16x8*)(lds + PG8_SA(b, h) + aoff + m * 2048 + k * 1024); } while (0)
; #define PG8_LDB(dst, b, h) do { _Pragma("unroll") for (int n = 0; n < 2; ++n) _Pragma("unroll") for (int k = 0; k < 2; ++k) dst[n][k] = *(const PG8_LAS bf16x8*)(lds + PG8_SB(b, h) + boff + n * 2048 + k * 1024); } while (0)
; #define PG8_MMA(ai, bj, At, Bt) do { __builtin_amdgcn_s_setprio(1); _Pragma("unroll") for (int m = 0; m < 4; ++m) _Pragma("unroll") for (int n = 0; n < 2; ++n) _Pragma("unroll") for (int k = 0; k < 2; ++k) \
;         acc[ai][bj][m][n] = __builtin_amdgcn_mfma_f32_16x16x32_bf16(Bt[n][k], At[m][k], acc[ai][bj][m][n], 0, 0, 0); __builtin_amdgcn_s_setprio(0); } while (0)
; #define PG8_WAIT_V(n) asm volatile("s_waitcnt vmcnt(" #n ")" ::: "memory")
; #define PG8_WAIT_L(n) asm volatile("s_waitcnt lgkmcnt(" #n ")" ::: "memory")
; #define PG8_BAR __builtin_amdgcn_s_barrier()
; #define PG8_SCHED __builtin_amdgcn_sched_barrier(0)
; template <class Epi, class Sched, bool ALIGN_EPI = false, bool SP2 = false>
; __device__ __forceinline__ void gemm_phase(PG8_LAS unsigned char* lds, const Gemm g, const Sched& S, const Epi& E, int wave_sgpr) {
;     ...
;             PG8_LDB(B0, 0, 0); PG8_LDB(B1, 0, 1); PG8_SCHED; PG8_LDA(At, 0, 0); PG8_STAGE(PG8_SA(1, 1), a1 + hstepA, voffA);
;             PG8_WAIT_V(8); PG8_WAIT_L(0); PG8_BAR; PG8_MMA(0, 0, At, B0); PG8_MMA(0, 1, At, B1); PG8_BAR; PG8_SCHED;
;             PG8_LDA(At, 0, 1); PG8_STAGE(PG8_SB(0, 0), b2, voffB); PG8_STAGE(PG8_SB(0, 1), b2 + hstepB, voffB); PG8_STAGE(PG8_SA(0, 0), a2, voffA);
.LBB0_1676:
	ds_read_b128 v[146:149], v157
	ds_read_b128 v[150:153], v157 offset:1024
	ds_read_b128 v[160:163], v157 offset:2048
	ds_read_b128 v[164:167], v157 offset:3072
	ds_read_b128 v[168:171], v158
	ds_read_b128 v[172:175], v158 offset:1024
	ds_read_b128 v[176:179], v158 offset:2048
	ds_read_b128 v[180:183], v158 offset:3072
	s_add_u32 s40, s38, 0xfffc0080
	s_addc_u32 s41, s39, -1
	s_cmp_eq_u32 s64, 12
	s_cselect_b32 s43, s7, s41
	s_cselect_b32 s42, s29, s40
	s_cselect_b32 s41, s27, s63
	s_cselect_b32 s40, s61, s62
	v_lshl_add_u64 v[216:217], s[38:39], 0, v[138:139]
	s_add_i32 m0, s37, 0xc000
	ds_read_b128 v[184:187], v159
	ds_read_b128 v[188:191], v159 offset:1024
	ds_read_b128 v[192:195], v159 offset:2048
	ds_read_b128 v[196:199], v159 offset:3072
	ds_read_b128 v[200:203], v159 offset:4096
	ds_read_b128 v[204:207], v159 offset:5120
	ds_read_b128 v[208:211], v159 offset:6144
	ds_read_b128 v[212:215], v159 offset:7168
	global_load_lds_dwordx4 v[216:217], off
	v_lshl_add_u64 v[216:217], s[38:39], 0, v[140:141]
	s_add_i32 m0, s37, 0xe000
	s_nop 0
	global_load_lds_dwordx4 v[216:217], off
	s_waitcnt vmcnt(8)
	s_waitcnt lgkmcnt(0)
	s_barrier
	s_setprio 1
	s_waitcnt lgkmcnt(0)
	v_mfma_f32_16x16x32_bf16 v[124:127], v[146:149], v[184:187], v[124:127]
	v_mfma_f32_16x16x32_bf16 v[120:123], v[160:163], v[184:187], v[120:123]
	v_mfma_f32_16x16x32_bf16 v[108:111], v[146:149], v[192:195], v[108:111]
	v_mfma_f32_16x16x32_bf16 v[104:107], v[160:163], v[192:195], v[104:107]
	v_mfma_f32_16x16x32_bf16 v[92:95], v[146:149], v[200:203], v[92:95]
	v_mfma_f32_16x16x32_bf16 v[88:91], v[160:163], v[200:203], v[88:91]
	v_mfma_f32_16x16x32_bf16 v[76:79], v[146:149], v[208:211], v[76:79]
	v_mfma_f32_16x16x32_bf16 v[72:75], v[160:163], v[208:211], v[72:75]
	v_mfma_f32_16x16x32_bf16 v[124:127], v[150:153], v[188:191], v[124:127]
	v_mfma_f32_16x16x32_bf16 v[120:123], v[164:167], v[188:191], v[120:123]
	v_mfma_f32_16x16x32_bf16 v[108:111], v[150:153], v[196:199], v[108:111]
	v_mfma_f32_16x16x32_bf16 v[104:107], v[164:167], v[196:199], v[104:107]
	v_mfma_f32_16x16x32_bf16 v[92:95], v[150:153], v[204:207], v[92:95]
	v_mfma_f32_16x16x32_bf16 v[88:91], v[164:167], v[204:207], v[88:91]
	v_mfma_f32_16x16x32_bf16 v[76:79], v[150:153], v[212:215], v[76:79]
	v_mfma_f32_16x16x32_bf16 v[72:75], v[164:167], v[212:215], v[72:75]
	v_mfma_f32_16x16x32_bf16 v[116:119], v[168:171], v[184:187], v[116:119]
	v_mfma_f32_16x16x32_bf16 v[112:115], v[176:179], v[184:187], v[112:115]
	v_mfma_f32_16x16x32_bf16 v[100:103], v[168:171], v[192:195], v[100:103]
	v_mfma_f32_16x16x32_bf16 v[96:99], v[176:179], v[192:195], v[96:99]
	v_mfma_f32_16x16x32_bf16 v[84:87], v[168:171], v[200:203], v[84:87]
	v_mfma_f32_16x16x32_bf16 v[80:83], v[176:179], v[200:203], v[80:83]
	v_mfma_f32_16x16x32_bf16 v[68:71], v[168:171], v[208:211], v[68:71]
	v_mfma_f32_16x16x32_bf16 v[64:67], v[176:179], v[208:211], v[64:67]
	v_mfma_f32_16x16x32_bf16 v[116:119], v[172:175], v[188:191], v[116:119]
	v_mfma_f32_16x16x32_bf16 v[112:115], v[180:183], v[188:191], v[112:115]
	v_mfma_f32_16x16x32_bf16 v[100:103], v[172:175], v[196:199], v[100:103]
	v_mfma_f32_16x16x32_bf16 v[96:99], v[180:183], v[196:199], v[96:99]
	v_mfma_f32_16x16x32_bf16 v[84:87], v[172:175], v[204:207], v[84:87]
	v_mfma_f32_16x16x32_bf16 v[80:83], v[180:183], v[204:207], v[80:83]
	v_mfma_f32_16x16x32_bf16 v[68:71], v[172:175], v[212:215], v[68:71]
	v_mfma_f32_16x16x32_bf16 v[64:67], v[180:183], v[212:215], v[64:67]
	s_setprio 0
	s_barrier
	s_add_i32 s65, s57, s45
	v_lshl_add_u64 v[216:217], s[40:41], 0, v[130:131]
	s_mov_b32 m0, s65
	ds_read_b128 v[184:187], v159 offset:16384
	ds_read_b128 v[188:191], v159 offset:17408
	ds_read_b128 v[192:195], v159 offset:18432
	ds_read_b128 v[196:199], v159 offset:19456
	ds_read_b128 v[200:203], v159 offset:20480
	ds_read_b128 v[204:207], v159 offset:21504
	ds_read_b128 v[208:211], v159 offset:22528
	ds_read_b128 v[212:215], v159 offset:23552
	global_load_lds_dwordx4 v[216:217], off
	s_add_i32 m0, s65, 0x2000
	s_add_u32 s66, s40, 0x40000
	v_lshl_add_u64 v[218:219], s[40:41], 0, v[134:135]
	s_addc_u32 s67, s41, 0
	s_add_i32 s65, s58, s45
	global_load_lds_dwordx4 v[218:219], off
	v_lshl_add_u64 v[220:221], s[66:67], 0, v[130:131]
	s_mov_b32 m0, s65
	v_lshl_add_u64 v[222:223], s[42:43], 0, v[132:133]
	global_load_lds_dwordx4 v[220:221], off
	v_lshl_add_u64 v[220:221], s[66:67], 0, v[134:135]
	s_add_i32 m0, s65, 0x2000
	s_nop 0
	global_load_lds_dwordx4 v[220:221], off
	v_lshl_add_u64 v[220:221], s[42:43], 0, v[128:129]
	s_mov_b32 m0, s37
	s_nop 0
	global_load_lds_dwordx4 v[220:221], off
	s_mov_b32 m0, s46
	s_nop 0
	global_load_lds_dwordx4 v[222:223], off
	s_waitcnt vmcnt(8)
	s_waitcnt lgkmcnt(0)
	s_barrier
; #define PG8_STAGE(bufoff, gbase, voff) do { _Pragma("unroll") for (int _i = 0; _i < 2; ++_i) \
;         __builtin_amdgcn_global_load_lds((const unsigned*)((const char*)(gbase) + (voff)[_i]), (PG8_LAS unsigned*)(lds + (bufoff) + ldsw + _i * 8192), 16, 0, 0); } while (0)
; #define PG8_LDA(dst, b, h) do { _Pragma("unroll") for (int m = 0; m < 4; ++m) _Pragma("unroll") for (int k = 0; k < 2; ++k) dst[m][k] = *(const PG8_LAS bf16x8*)(lds + PG8_SA(b, h) + aoff + m * 2048 + k * 1024); } while (0)
; #define PG8_LDB(dst, b, h) do { _Pragma("unroll") for (int n = 0; n < 2; ++n) _Pragma("unroll") for (int k = 0; k < 2; ++k) dst[n][k] = *(const PG8_LAS bf16x8*)(lds + PG8_SB(b, h) + boff + n * 2048 + k * 1024); } while (0)
; #define PG8_MMA(ai, bj, At, Bt) do { __builtin_amdgcn_s_setprio(1); _Pragma("unroll") for (int m = 0; m < 4; ++m) _Pragma("unroll") for (int n = 0; n < 2; ++n) _Pragma("unroll") for (int k = 0; k < 2; ++k) \
;         acc[ai][bj][m][n] = __builtin_amdgcn_mfma_f32_16x16x32_bf16(Bt[n][k], At[m][k], acc[ai][bj][m][n], 0, 0, 0); __builtin_amdgcn_s_setprio(0); } while (0)
; #define PG8_WAIT_V(n) asm volatile("s_waitcnt vmcnt(" #n ")" ::: "memory")
; #define PG8_WAIT_L(n) asm volatile("s_waitcnt lgkmcnt(" #n ")" ::: "memory")
; #define PG8_BAR __builtin_amdgcn_s_barrier()
; #define PG8_SCHED __builtin_amdgcn_sched_barrier(0)
; template <class Epi, class Sched, bool ALIGN_EPI = false, bool SP2 = false>
; __device__ __forceinline__ void gemm_phase(PG8_LAS unsigned char* lds, const Gemm g, const Sched& S, const Epi& E, int wave_sgpr) {
;     ...
;             PG8_WAIT_V(8); PG8_WAIT_L(0); PG8_BAR; PG8_MMA(1, 0, At, B0); PG8_MMA(1, 1, At, B1); PG8_BAR; PG8_SCHED;
;             PG8_LDB(B0, 1, 0); PG8_LDB(B1, 1, 1); PG8_SCHED; PG8_LDA(At, 1, 0); PG8_STAGE(PG8_SA(0, 1), a2 + hstepA, voffA);
;             PG8_WAIT_V(8); PG8_WAIT_L(0); PG8_BAR; PG8_MMA(0, 0, At, B0); PG8_MMA(0, 1, At, B1); PG8_BAR; PG8_SCHED;
	s_setprio 1
	s_waitcnt lgkmcnt(0)
	v_mfma_f32_16x16x32_bf16 v[60:63], v[146:149], v[184:187], v[60:63]
	v_mfma_f32_16x16x32_bf16 v[56:59], v[160:163], v[184:187], v[56:59]
	v_mfma_f32_16x16x32_bf16 v[44:47], v[146:149], v[192:195], v[44:47]
	v_mfma_f32_16x16x32_bf16 v[40:43], v[160:163], v[192:195], v[40:43]
	v_mfma_f32_16x16x32_bf16 v[28:31], v[146:149], v[200:203], v[28:31]
	v_mfma_f32_16x16x32_bf16 v[24:27], v[160:163], v[200:203], v[24:27]
	v_mfma_f32_16x16x32_bf16 v[12:15], v[146:149], v[208:211], v[12:15]
	v_mfma_f32_16x16x32_bf16 v[8:11], v[160:163], v[208:211], v[8:11]
	v_mfma_f32_16x16x32_bf16 v[60:63], v[150:153], v[188:191], v[60:63]
	v_mfma_f32_16x16x32_bf16 v[56:59], v[164:167], v[188:191], v[56:59]
	v_mfma_f32_16x16x32_bf16 v[44:47], v[150:153], v[196:199], v[44:47]
	v_mfma_f32_16x16x32_bf16 v[40:43], v[164:167], v[196:199], v[40:43]
	v_mfma_f32_16x16x32_bf16 v[28:31], v[150:153], v[204:207], v[28:31]
	v_mfma_f32_16x16x32_bf16 v[24:27], v[164:167], v[204:207], v[24:27]
	v_mfma_f32_16x16x32_bf16 v[12:15], v[150:153], v[212:215], v[12:15]
	v_mfma_f32_16x16x32_bf16 v[8:11], v[164:167], v[212:215], v[8:11]
	v_mfma_f32_16x16x32_bf16 v[52:55], v[168:171], v[184:187], v[52:55]
	v_mfma_f32_16x16x32_bf16 v[48:51], v[176:179], v[184:187], v[48:51]
	v_mfma_f32_16x16x32_bf16 v[36:39], v[168:171], v[192:195], v[36:39]
	v_mfma_f32_16x16x32_bf16 v[32:35], v[176:179], v[192:195], v[32:35]
	v_mfma_f32_16x16x32_bf16 v[20:23], v[168:171], v[200:203], v[20:23]
	v_mfma_f32_16x16x32_bf16 v[16:19], v[176:179], v[200:203], v[16:19]
	v_mfma_f32_16x16x32_bf16 v[4:7], v[168:171], v[208:211], v[4:7]
	v_mfma_f32_16x16x32_bf16 v[0:3], v[176:179], v[208:211], v[0:3]
	v_mfma_f32_16x16x32_bf16 v[52:55], v[172:175], v[188:191], v[52:55]
	v_mfma_f32_16x16x32_bf16 v[48:51], v[180:183], v[188:191], v[48:51]
	v_mfma_f32_16x16x32_bf16 v[36:39], v[172:175], v[196:199], v[36:39]
	v_mfma_f32_16x16x32_bf16 v[32:35], v[180:183], v[196:199], v[32:35]
	v_mfma_f32_16x16x32_bf16 v[20:23], v[172:175], v[204:207], v[20:23]
	v_mfma_f32_16x16x32_bf16 v[16:19], v[180:183], v[204:207], v[16:19]
	v_mfma_f32_16x16x32_bf16 v[4:7], v[172:175], v[212:215], v[4:7]
	v_mfma_f32_16x16x32_bf16 v[0:3], v[180:183], v[212:215], v[0:3]
	s_setprio 0
	s_barrier
	s_add_i32 s65, 0, 0x18000
	v_add_u32_e32 v136, s65, v155
	s_add_i32 s66, 0, 0x1c000
	ds_read_b128 v[146:149], v136
	ds_read_b128 v[150:153], v136 offset:1024
	ds_read_b128 v[160:163], v136 offset:2048
	ds_read_b128 v[164:167], v136 offset:3072
	v_add_u32_e32 v136, s66, v155
	ds_read_b128 v[168:171], v136
	ds_read_b128 v[172:175], v136 offset:1024
	ds_read_b128 v[176:179], v136 offset:2048
	ds_read_b128 v[180:183], v136 offset:3072
	s_add_u32 s42, s42, 0x40000
	s_addc_u32 s43, s43, 0
	s_mov_b32 m0, s47
	v_lshl_add_u64 v[224:225], s[42:43], 0, v[128:129]
	ds_read_b128 v[184:187], v159 offset:32768
	ds_read_b128 v[188:191], v159 offset:33792
	ds_read_b128 v[192:195], v159 offset:34816
	ds_read_b128 v[196:199], v159 offset:35840
	ds_read_b128 v[200:203], v159 offset:36864
	ds_read_b128 v[204:207], v159 offset:37888
	ds_read_b128 v[208:211], v159 offset:38912
	ds_read_b128 v[212:215], v159 offset:39936
	global_load_lds_dwordx4 v[224:225], off
	v_lshl_add_u64 v[224:225], s[42:43], 0, v[132:133]
	s_mov_b32 m0, s48
	s_nop 0
	global_load_lds_dwordx4 v[224:225], off
	s_waitcnt vmcnt(8)
	s_waitcnt lgkmcnt(0)
	s_barrier
	s_setprio 1
	s_waitcnt lgkmcnt(0)
	v_mfma_f32_16x16x32_bf16 v[124:127], v[146:149], v[184:187], v[124:127]
	v_mfma_f32_16x16x32_bf16 v[120:123], v[160:163], v[184:187], v[120:123]
	v_mfma_f32_16x16x32_bf16 v[108:111], v[146:149], v[192:195], v[108:111]
	v_mfma_f32_16x16x32_bf16 v[104:107], v[160:163], v[192:195], v[104:107]
	v_mfma_f32_16x16x32_bf16 v[92:95], v[146:149], v[200:203], v[92:95]
	v_mfma_f32_16x16x32_bf16 v[88:91], v[160:163], v[200:203], v[88:91]
	v_mfma_f32_16x16x32_bf16 v[76:79], v[146:149], v[208:211], v[76:79]
	v_mfma_f32_16x16x32_bf16 v[72:75], v[160:163], v[208:211], v[72:75]
	v_mfma_f32_16x16x32_bf16 v[124:127], v[150:153], v[188:191], v[124:127]
	v_mfma_f32_16x16x32_bf16 v[120:123], v[164:167], v[188:191], v[120:123]
	v_mfma_f32_16x16x32_bf16 v[108:111], v[150:153], v[196:199], v[108:111]
	v_mfma_f32_16x16x32_bf16 v[104:107], v[164:167], v[196:199], v[104:107]
	v_mfma_f32_16x16x32_bf16 v[92:95], v[150:153], v[204:207], v[92:95]
	v_mfma_f32_16x16x32_bf16 v[88:91], v[164:167], v[204:207], v[88:91]
	v_mfma_f32_16x16x32_bf16 v[76:79], v[150:153], v[212:215], v[76:79]
	v_mfma_f32_16x16x32_bf16 v[72:75], v[164:167], v[212:215], v[72:75]
	v_mfma_f32_16x16x32_bf16 v[116:119], v[168:171], v[184:187], v[116:119]
	v_mfma_f32_16x16x32_bf16 v[112:115], v[176:179], v[184:187], v[112:115]
	v_mfma_f32_16x16x32_bf16 v[100:103], v[168:171], v[192:195], v[100:103]
	v_mfma_f32_16x16x32_bf16 v[96:99], v[176:179], v[192:195], v[96:99]
	v_mfma_f32_16x16x32_bf16 v[84:87], v[168:171], v[200:203], v[84:87]
	v_mfma_f32_16x16x32_bf16 v[80:83], v[176:179], v[200:203], v[80:83]
	v_mfma_f32_16x16x32_bf16 v[68:71], v[168:171], v[208:211], v[68:71]
	v_mfma_f32_16x16x32_bf16 v[64:67], v[176:179], v[208:211], v[64:67]
	v_mfma_f32_16x16x32_bf16 v[116:119], v[172:175], v[188:191], v[116:119]
	v_mfma_f32_16x16x32_bf16 v[112:115], v[180:183], v[188:191], v[112:115]
	v_mfma_f32_16x16x32_bf16 v[100:103], v[172:175], v[196:199], v[100:103]
	v_mfma_f32_16x16x32_bf16 v[96:99], v[180:183], v[196:199], v[96:99]
	v_mfma_f32_16x16x32_bf16 v[84:87], v[172:175], v[204:207], v[84:87]
	v_mfma_f32_16x16x32_bf16 v[80:83], v[180:183], v[204:207], v[80:83]
	v_mfma_f32_16x16x32_bf16 v[68:71], v[172:175], v[212:215], v[68:71]
	v_mfma_f32_16x16x32_bf16 v[64:67], v[180:183], v[212:215], v[64:67]
	s_setprio 0
	s_barrier
; #define PG8_STAGE(bufoff, gbase, voff) do { _Pragma("unroll") for (int _i = 0; _i < 2; ++_i) \
;         __builtin_amdgcn_global_load_lds((const unsigned*)((const char*)(gbase) + (voff)[_i]), (PG8_LAS unsigned*)(lds + (bufoff) + ldsw + _i * 8192), 16, 0, 0); } while (0)
; #define PG8_LDA(dst, b, h) do { _Pragma("unroll") for (int m = 0; m < 4; ++m) _Pragma("unroll") for (int k = 0; k < 2; ++k) dst[m][k] = *(const PG8_LAS bf16x8*)(lds + PG8_SA(b, h) + aoff + m * 2048 + k * 1024); } while (0)
; #define PG8_MMA(ai, bj, At, Bt) do { __builtin_amdgcn_s_setprio(1); _Pragma("unroll") for (int m = 0; m < 4; ++m) _Pragma("unroll") for (int n = 0; n < 2; ++n) _Pragma("unroll") for (int k = 0; k < 2; ++k) \
;         acc[ai][bj][m][n] = __builtin_amdgcn_mfma_f32_16x16x32_bf16(Bt[n][k], At[m][k], acc[ai][bj][m][n], 0, 0, 0); __builtin_amdgcn_s_setprio(0); } while (0)
; #define PG8_WAIT_V(n) asm volatile("s_waitcnt vmcnt(" #n ")" ::: "memory")
; #define PG8_WAIT_L(n) asm volatile("s_waitcnt lgkmcnt(" #n ")" ::: "memory")
; #define PG8_BAR __builtin_amdgcn_s_barrier()
; #define PG8_SCHED __builtin_amdgcn_sched_barrier(0)
; template <class Epi, class Sched, bool ALIGN_EPI = false, bool SP2 = false>
; __device__ __forceinline__ void gemm_phase(PG8_LAS unsigned char* lds, const Gemm g, const Sched& S, const Epi& E, int wave_sgpr) {
;     ...
;         for (int t = 0; t < nt; t += 2) {
;             const bool last = (t == nt - 2);
;             const char* a1 = cA + (size_t)(t + 1) * kstep;
;             const char* a2 = last ? nA : cA + (size_t)(t + 2) * kstep; const char* b2 = last ? nB : cB + (size_t)(t + 2) * kstep;
;     ...
;             PG8_LDA(At, 1, 1); PG8_STAGE(PG8_SB(1, 0), b3, voffB); PG8_STAGE(PG8_SB(1, 1), b3 + hstepB, voffB); PG8_STAGE(PG8_SA(1, 0), a3, voffA);
;             PG8_WAIT_V(8); PG8_WAIT_L(0); PG8_BAR; PG8_MMA(1, 0, At, B0); PG8_MMA(1, 1, At, B1); PG8_BAR; PG8_SCHED;
	s_add_i32 s42, s65, s45
	v_lshl_add_u64 v[216:217], v[216:217], 0, s[18:19]
	s_mov_b32 m0, s42
	ds_read_b128 v[184:187], v159 offset:49152
	ds_read_b128 v[188:191], v159 offset:50176
	ds_read_b128 v[192:195], v159 offset:51200
	ds_read_b128 v[196:199], v159 offset:52224
	ds_read_b128 v[200:203], v159 offset:53248
	ds_read_b128 v[204:207], v159 offset:54272
	ds_read_b128 v[208:211], v159 offset:55296
	ds_read_b128 v[212:215], v159 offset:56320
	global_load_lds_dwordx4 v[216:217], off
	s_add_i32 m0, s42, 0x2000
	s_add_u32 s40, s40, 0x40080
	v_lshl_add_u64 v[216:217], v[218:219], 0, s[18:19]
	s_addc_u32 s41, s41, 0
	s_add_i32 s42, s66, s45
	global_load_lds_dwordx4 v[216:217], off
	v_lshl_add_u64 v[216:217], s[40:41], 0, v[130:131]
	s_mov_b32 m0, s42
	s_nop 0
	global_load_lds_dwordx4 v[216:217], off
	v_lshl_add_u64 v[216:217], s[40:41], 0, v[134:135]
	s_add_i32 m0, s42, 0x2000
	s_nop 0
	global_load_lds_dwordx4 v[216:217], off
	v_lshl_add_u64 v[216:217], v[220:221], 0, s[18:19]
	s_mov_b32 m0, s53
	s_nop 0
	global_load_lds_dwordx4 v[216:217], off
	v_lshl_add_u64 v[216:217], v[222:223], 0, s[18:19]
	s_mov_b32 m0, s54
	s_nop 0
	global_load_lds_dwordx4 v[216:217], off
	s_waitcnt vmcnt(8)
	s_waitcnt lgkmcnt(0)
	s_barrier
	s_setprio 1
	s_waitcnt lgkmcnt(0)
	v_mfma_f32_16x16x32_bf16 v[60:63], v[146:149], v[184:187], v[60:63]
	v_mfma_f32_16x16x32_bf16 v[56:59], v[160:163], v[184:187], v[56:59]
	v_mfma_f32_16x16x32_bf16 v[44:47], v[146:149], v[192:195], v[44:47]
	v_mfma_f32_16x16x32_bf16 v[40:43], v[160:163], v[192:195], v[40:43]
	v_mfma_f32_16x16x32_bf16 v[28:31], v[146:149], v[200:203], v[28:31]
	v_mfma_f32_16x16x32_bf16 v[24:27], v[160:163], v[200:203], v[24:27]
	v_mfma_f32_16x16x32_bf16 v[12:15], v[146:149], v[208:211], v[12:15]
	v_mfma_f32_16x16x32_bf16 v[8:11], v[160:163], v[208:211], v[8:11]
	v_mfma_f32_16x16x32_bf16 v[60:63], v[150:153], v[188:191], v[60:63]
	v_mfma_f32_16x16x32_bf16 v[56:59], v[164:167], v[188:191], v[56:59]
	v_mfma_f32_16x16x32_bf16 v[44:47], v[150:153], v[196:199], v[44:47]
	v_mfma_f32_16x16x32_bf16 v[40:43], v[164:167], v[196:199], v[40:43]
	v_mfma_f32_16x16x32_bf16 v[28:31], v[150:153], v[204:207], v[28:31]
	v_mfma_f32_16x16x32_bf16 v[24:27], v[164:167], v[204:207], v[24:27]
	v_mfma_f32_16x16x32_bf16 v[12:15], v[150:153], v[212:215], v[12:15]
	v_mfma_f32_16x16x32_bf16 v[8:11], v[164:167], v[212:215], v[8:11]
	v_mfma_f32_16x16x32_bf16 v[52:55], v[168:171], v[184:187], v[52:55]
	v_mfma_f32_16x16x32_bf16 v[48:51], v[176:179], v[184:187], v[48:51]
	v_mfma_f32_16x16x32_bf16 v[36:39], v[168:171], v[192:195], v[36:39]
	v_mfma_f32_16x16x32_bf16 v[32:35], v[176:179], v[192:195], v[32:35]
	v_mfma_f32_16x16x32_bf16 v[20:23], v[168:171], v[200:203], v[20:23]
	v_mfma_f32_16x16x32_bf16 v[16:19], v[176:179], v[200:203], v[16:19]
	v_mfma_f32_16x16x32_bf16 v[4:7], v[168:171], v[208:211], v[4:7]
	v_mfma_f32_16x16x32_bf16 v[0:3], v[176:179], v[208:211], v[0:3]
	v_mfma_f32_16x16x32_bf16 v[52:55], v[172:175], v[188:191], v[52:55]
	v_mfma_f32_16x16x32_bf16 v[48:51], v[180:183], v[188:191], v[48:51]
	v_mfma_f32_16x16x32_bf16 v[36:39], v[172:175], v[196:199], v[36:39]
	v_mfma_f32_16x16x32_bf16 v[32:35], v[180:183], v[196:199], v[32:35]
	v_mfma_f32_16x16x32_bf16 v[20:23], v[172:175], v[204:207], v[20:23]
	v_mfma_f32_16x16x32_bf16 v[16:19], v[180:183], v[204:207], v[16:19]
	v_mfma_f32_16x16x32_bf16 v[4:7], v[172:175], v[212:215], v[4:7]
	v_mfma_f32_16x16x32_bf16 v[0:3], v[180:183], v[212:215], v[0:3]
	s_setprio 0
	s_barrier
	s_add_i32 s64, s64, 2
	s_add_u32 s38, s38, 0x100
	s_addc_u32 s39, s39, 0
	s_add_u32 s62, s62, 0x100
	s_addc_u32 s63, s63, 0
	s_cmp_gt_u32 s64, 13
	s_cbranch_scc0 .LBB0_1676
	s_and_b64 vcc, exec, s[20:21]
	s_cbranch_vccz .LBB0_1679
	s_barrier

; #define PG8_STAGE(bufoff, gbase, voff) do { _Pragma("unroll") for (int _i = 0; _i < 2; ++_i) \
;         __builtin_amdgcn_global_load_lds((const unsigned*)((const char*)(gbase) + (voff)[_i]), (PG8_LAS unsigned*)(lds + (bufoff) + ldsw + _i * 8192), 16, 0, 0); } while (0)
; #define PG8_LDA(dst, b, h) do { _Pragma("unroll") for (int m = 0; m < 4; ++m) _Pragma("unroll") for (int k = 0; k < 2; ++k) dst[m][k] = *(const PG8_LAS bf16x8*)(lds + PG8_SA(b, h) + aoff + m * 2048 + k * 1024); } while (0)
; #define PG8_LDB(dst, b, h) do { _Pragma("unroll") for (int n = 0; n < 2; ++n) _Pragma("unroll") for (int k = 0; k < 2; ++k) dst[n][k] = *(const PG8_LAS bf16x8*)(lds + PG8_SB(b, h) + boff + n * 2048 + k * 1024); } while (0)
; #define PG8_MMA(ai, bj, At, Bt) do { __builtin_amdgcn_s_setprio(1); _Pragma("unroll") for (int m = 0; m < 4; ++m) _Pragma("unroll") for (int n = 0; n < 2; ++n) _Pragma("unroll") for (int k = 0; k < 2; ++k) \
;         acc[ai][bj][m][n] = __builtin_amdgcn_mfma_f32_16x16x32_bf16(Bt[n][k], At[m][k], acc[ai][bj][m][n], 0, 0, 0); __builtin_amdgcn_s_setprio(0); } while (0)
; #define PG8_WAIT_V(n) asm volatile("s_waitcnt vmcnt(" #n ")" ::: "memory")
; #define PG8_WAIT_L(n) asm volatile("s_waitcnt lgkmcnt(" #n ")" ::: "memory")
; #define PG8_BAR __builtin_amdgcn_s_barrier()
; #define PG8_SCHED __builtin_amdgcn_sched_barrier(0)
; template <class Epi, class Sched, bool ALIGN_EPI = false, bool SP2 = false>
; __device__ __forceinline__ void gemm_phase(PG8_LAS unsigned char* lds, const Gemm g, const Sched& S, const Epi& E, int wave_sgpr) {
;     ...
;             PG8_LDB(B0, 0, 0); PG8_LDB(B1, 0, 1); PG8_SCHED; PG8_LDA(At, 0, 0); PG8_STAGE(PG8_SA(1, 1), a1 + hstepA, voffA);
;             PG8_WAIT_V(8); PG8_WAIT_L(0); PG8_BAR; PG8_MMA(0, 0, At, B0); PG8_MMA(0, 1, At, B1); PG8_BAR; PG8_SCHED;
;             PG8_LDA(At, 0, 1); PG8_STAGE(PG8_SB(0, 0), b2, voffB); PG8_STAGE(PG8_SB(0, 1), b2 + hstepB, voffB); PG8_STAGE(PG8_SA(0, 0), a2, voffA);
.LBB0_1855:
	ds_read_b128 v[152:155], v149
	ds_read_b128 v[156:159], v149 offset:1024
	ds_read_b128 v[160:163], v149 offset:2048
	ds_read_b128 v[164:167], v149 offset:3072
	ds_read_b128 v[168:171], v150
	ds_read_b128 v[172:175], v150 offset:1024
	ds_read_b128 v[176:179], v150 offset:2048
	ds_read_b128 v[180:183], v150 offset:3072
	s_add_u32 s26, s24, 0xfffc0080
	s_addc_u32 s27, s25, -1
	s_cmp_eq_u32 s50, 12
	s_cselect_b32 s29, s17, s27
	s_cselect_b32 s28, s46, s26
	s_cselect_b32 s27, s15, s49
	s_cselect_b32 s26, s47, s48
	v_lshl_add_u64 v[144:145], s[24:25], 0, v[136:137]
	s_add_i32 m0, s23, 0xc000
	ds_read_b128 v[184:187], v151
	ds_read_b128 v[188:191], v151 offset:1024
	ds_read_b128 v[192:195], v151 offset:2048
	ds_read_b128 v[196:199], v151 offset:3072
	ds_read_b128 v[200:203], v151 offset:4096
	ds_read_b128 v[204:207], v151 offset:5120
	ds_read_b128 v[208:211], v151 offset:6144
	ds_read_b128 v[212:215], v151 offset:7168
	global_load_lds_dwordx4 v[144:145], off
	v_lshl_add_u64 v[144:145], s[24:25], 0, v[138:139]
	s_add_i32 m0, s23, 0xe000
	s_nop 0
	global_load_lds_dwordx4 v[144:145], off
	s_waitcnt vmcnt(8)
	s_waitcnt lgkmcnt(0)
	s_barrier
	s_setprio 1
	s_waitcnt lgkmcnt(0)
	v_mfma_f32_16x16x32_bf16 v[124:127], v[152:155], v[184:187], v[124:127]
	v_mfma_f32_16x16x32_bf16 v[120:123], v[160:163], v[184:187], v[120:123]
	v_mfma_f32_16x16x32_bf16 v[108:111], v[152:155], v[192:195], v[108:111]
	v_mfma_f32_16x16x32_bf16 v[104:107], v[160:163], v[192:195], v[104:107]
	v_mfma_f32_16x16x32_bf16 v[92:95], v[152:155], v[200:203], v[92:95]
	v_mfma_f32_16x16x32_bf16 v[88:91], v[160:163], v[200:203], v[88:91]
	v_mfma_f32_16x16x32_bf16 v[76:79], v[152:155], v[208:211], v[76:79]
	v_mfma_f32_16x16x32_bf16 v[72:75], v[160:163], v[208:211], v[72:75]
	v_mfma_f32_16x16x32_bf16 v[124:127], v[156:159], v[188:191], v[124:127]
	v_mfma_f32_16x16x32_bf16 v[120:123], v[164:167], v[188:191], v[120:123]
	v_mfma_f32_16x16x32_bf16 v[108:111], v[156:159], v[196:199], v[108:111]
	v_mfma_f32_16x16x32_bf16 v[104:107], v[164:167], v[196:199], v[104:107]
	v_mfma_f32_16x16x32_bf16 v[92:95], v[156:159], v[204:207], v[92:95]
	v_mfma_f32_16x16x32_bf16 v[88:91], v[164:167], v[204:207], v[88:91]
	v_mfma_f32_16x16x32_bf16 v[76:79], v[156:159], v[212:215], v[76:79]
	v_mfma_f32_16x16x32_bf16 v[72:75], v[164:167], v[212:215], v[72:75]
	v_mfma_f32_16x16x32_bf16 v[116:119], v[168:171], v[184:187], v[116:119]
	v_mfma_f32_16x16x32_bf16 v[112:115], v[176:179], v[184:187], v[112:115]
	v_mfma_f32_16x16x32_bf16 v[100:103], v[168:171], v[192:195], v[100:103]
	v_mfma_f32_16x16x32_bf16 v[96:99], v[176:179], v[192:195], v[96:99]
	v_mfma_f32_16x16x32_bf16 v[84:87], v[168:171], v[200:203], v[84:87]
	v_mfma_f32_16x16x32_bf16 v[80:83], v[176:179], v[200:203], v[80:83]
	v_mfma_f32_16x16x32_bf16 v[68:71], v[168:171], v[208:211], v[68:71]
	v_mfma_f32_16x16x32_bf16 v[64:67], v[176:179], v[208:211], v[64:67]
	v_mfma_f32_16x16x32_bf16 v[116:119], v[172:175], v[188:191], v[116:119]
	v_mfma_f32_16x16x32_bf16 v[112:115], v[180:183], v[188:191], v[112:115]
	v_mfma_f32_16x16x32_bf16 v[100:103], v[172:175], v[196:199], v[100:103]
	v_mfma_f32_16x16x32_bf16 v[96:99], v[180:183], v[196:199], v[96:99]
	v_mfma_f32_16x16x32_bf16 v[84:87], v[172:175], v[204:207], v[84:87]
	v_mfma_f32_16x16x32_bf16 v[80:83], v[180:183], v[204:207], v[80:83]
	v_mfma_f32_16x16x32_bf16 v[68:71], v[172:175], v[212:215], v[68:71]
	v_mfma_f32_16x16x32_bf16 v[64:67], v[180:183], v[212:215], v[64:67]
	s_setprio 0
	s_barrier
	s_add_i32 s51, s42, s34
	v_lshl_add_u64 v[144:145], s[26:27], 0, v[130:131]
	s_mov_b32 m0, s51
	ds_read_b128 v[184:187], v151 offset:16384
	ds_read_b128 v[188:191], v151 offset:17408
	ds_read_b128 v[192:195], v151 offset:18432
	ds_read_b128 v[196:199], v151 offset:19456
	ds_read_b128 v[200:203], v151 offset:20480
	ds_read_b128 v[204:207], v151 offset:21504
	ds_read_b128 v[208:211], v151 offset:22528
	ds_read_b128 v[212:215], v151 offset:23552
	global_load_lds_dwordx4 v[144:145], off
	s_add_i32 m0, s51, 0x2000
	s_add_u32 s52, s26, 0x40000
	v_lshl_add_u64 v[216:217], s[26:27], 0, v[134:135]
	s_addc_u32 s53, s27, 0
	s_add_i32 s51, s43, s34
	global_load_lds_dwordx4 v[216:217], off
	v_lshl_add_u64 v[218:219], s[52:53], 0, v[130:131]
	s_mov_b32 m0, s51
	v_lshl_add_u64 v[220:221], s[28:29], 0, v[132:133]
	global_load_lds_dwordx4 v[218:219], off
	v_lshl_add_u64 v[218:219], s[52:53], 0, v[134:135]
	s_add_i32 m0, s51, 0x2000
	s_nop 0
	global_load_lds_dwordx4 v[218:219], off
	v_lshl_add_u64 v[218:219], s[28:29], 0, v[128:129]
	s_mov_b32 m0, s23
	s_nop 0
	global_load_lds_dwordx4 v[218:219], off
	s_mov_b32 m0, s35
	s_nop 0
	global_load_lds_dwordx4 v[220:221], off
	s_waitcnt vmcnt(8)
	s_waitcnt lgkmcnt(0)
	s_barrier
; #define PG8_STAGE(bufoff, gbase, voff) do { _Pragma("unroll") for (int _i = 0; _i < 2; ++_i) \
;         __builtin_amdgcn_global_load_lds((const unsigned*)((const char*)(gbase) + (voff)[_i]), (PG8_LAS unsigned*)(lds + (bufoff) + ldsw + _i * 8192), 16, 0, 0); } while (0)
; #define PG8_LDA(dst, b, h) do { _Pragma("unroll") for (int m = 0; m < 4; ++m) _Pragma("unroll") for (int k = 0; k < 2; ++k) dst[m][k] = *(const PG8_LAS bf16x8*)(lds + PG8_SA(b, h) + aoff + m * 2048 + k * 1024); } while (0)
; #define PG8_LDB(dst, b, h) do { _Pragma("unroll") for (int n = 0; n < 2; ++n) _Pragma("unroll") for (int k = 0; k < 2; ++k) dst[n][k] = *(const PG8_LAS bf16x8*)(lds + PG8_SB(b, h) + boff + n * 2048 + k * 1024); } while (0)
; #define PG8_MMA(ai, bj, At, Bt) do { __builtin_amdgcn_s_setprio(1); _Pragma("unroll") for (int m = 0; m < 4; ++m) _Pragma("unroll") for (int n = 0; n < 2; ++n) _Pragma("unroll") for (int k = 0; k < 2; ++k) \
;         acc[ai][bj][m][n] = __builtin_amdgcn_mfma_f32_16x16x32_bf16(Bt[n][k], At[m][k], acc[ai][bj][m][n], 0, 0, 0); __builtin_amdgcn_s_setprio(0); } while (0)
; #define PG8_WAIT_V(n) asm volatile("s_waitcnt vmcnt(" #n ")" ::: "memory")
; #define PG8_WAIT_L(n) asm volatile("s_waitcnt lgkmcnt(" #n ")" ::: "memory")
; #define PG8_BAR __builtin_amdgcn_s_barrier()
; #define PG8_SCHED __builtin_amdgcn_sched_barrier(0)
; template <class Epi, class Sched, bool ALIGN_EPI = false, bool SP2 = false>
; __device__ __forceinline__ void gemm_phase(PG8_LAS unsigned char* lds, const Gemm g, const Sched& S, const Epi& E, int wave_sgpr) {
;     ...
;             PG8_WAIT_V(8); PG8_WAIT_L(0); PG8_BAR; PG8_MMA(1, 0, At, B0); PG8_MMA(1, 1, At, B1); PG8_BAR; PG8_SCHED;
;             PG8_LDB(B0, 1, 0); PG8_LDB(B1, 1, 1); PG8_SCHED; PG8_LDA(At, 1, 0); PG8_STAGE(PG8_SA(0, 1), a2 + hstepA, voffA);
;             PG8_WAIT_V(8); PG8_WAIT_L(0); PG8_BAR; PG8_MMA(0, 0, At, B0); PG8_MMA(0, 1, At, B1); PG8_BAR; PG8_SCHED;
	s_setprio 1
	s_waitcnt lgkmcnt(0)
	v_mfma_f32_16x16x32_bf16 v[60:63], v[152:155], v[184:187], v[60:63]
	v_mfma_f32_16x16x32_bf16 v[56:59], v[160:163], v[184:187], v[56:59]
	v_mfma_f32_16x16x32_bf16 v[44:47], v[152:155], v[192:195], v[44:47]
	v_mfma_f32_16x16x32_bf16 v[40:43], v[160:163], v[192:195], v[40:43]
	v_mfma_f32_16x16x32_bf16 v[28:31], v[152:155], v[200:203], v[28:31]
	v_mfma_f32_16x16x32_bf16 v[24:27], v[160:163], v[200:203], v[24:27]
	v_mfma_f32_16x16x32_bf16 v[12:15], v[152:155], v[208:211], v[12:15]
	v_mfma_f32_16x16x32_bf16 v[8:11], v[160:163], v[208:211], v[8:11]
	v_mfma_f32_16x16x32_bf16 v[60:63], v[156:159], v[188:191], v[60:63]
	v_mfma_f32_16x16x32_bf16 v[56:59], v[164:167], v[188:191], v[56:59]
	v_mfma_f32_16x16x32_bf16 v[44:47], v[156:159], v[196:199], v[44:47]
	v_mfma_f32_16x16x32_bf16 v[40:43], v[164:167], v[196:199], v[40:43]
	v_mfma_f32_16x16x32_bf16 v[28:31], v[156:159], v[204:207], v[28:31]
	v_mfma_f32_16x16x32_bf16 v[24:27], v[164:167], v[204:207], v[24:27]
	v_mfma_f32_16x16x32_bf16 v[12:15], v[156:159], v[212:215], v[12:15]
	v_mfma_f32_16x16x32_bf16 v[8:11], v[164:167], v[212:215], v[8:11]
	v_mfma_f32_16x16x32_bf16 v[52:55], v[168:171], v[184:187], v[52:55]
	v_mfma_f32_16x16x32_bf16 v[48:51], v[176:179], v[184:187], v[48:51]
	v_mfma_f32_16x16x32_bf16 v[36:39], v[168:171], v[192:195], v[36:39]
	v_mfma_f32_16x16x32_bf16 v[32:35], v[176:179], v[192:195], v[32:35]
	v_mfma_f32_16x16x32_bf16 v[20:23], v[168:171], v[200:203], v[20:23]
	v_mfma_f32_16x16x32_bf16 v[16:19], v[176:179], v[200:203], v[16:19]
	v_mfma_f32_16x16x32_bf16 v[4:7], v[168:171], v[208:211], v[4:7]
	v_mfma_f32_16x16x32_bf16 v[0:3], v[176:179], v[208:211], v[0:3]
	v_mfma_f32_16x16x32_bf16 v[52:55], v[172:175], v[188:191], v[52:55]
	v_mfma_f32_16x16x32_bf16 v[48:51], v[180:183], v[188:191], v[48:51]
	v_mfma_f32_16x16x32_bf16 v[36:39], v[172:175], v[196:199], v[36:39]
	v_mfma_f32_16x16x32_bf16 v[32:35], v[180:183], v[196:199], v[32:35]
	v_mfma_f32_16x16x32_bf16 v[20:23], v[172:175], v[204:207], v[20:23]
	v_mfma_f32_16x16x32_bf16 v[16:19], v[180:183], v[204:207], v[16:19]
	v_mfma_f32_16x16x32_bf16 v[4:7], v[172:175], v[212:215], v[4:7]
	v_mfma_f32_16x16x32_bf16 v[0:3], v[180:183], v[212:215], v[0:3]
	s_setprio 0
	s_barrier
	s_add_i32 s51, 0, 0x18000
	s_add_i32 s52, 0, 0x1c000
	v_add_u32_e32 v164, s51, v147
	v_add_u32_e32 v180, s52, v147
	ds_read_b128 v[152:155], v164
	ds_read_b128 v[156:159], v164 offset:1024
	ds_read_b128 v[160:163], v164 offset:2048
	ds_read_b128 v[164:167], v164 offset:3072
	ds_read_b128 v[168:171], v180
	ds_read_b128 v[172:175], v180 offset:1024
	ds_read_b128 v[176:179], v180 offset:2048
	ds_read_b128 v[180:183], v180 offset:3072
	s_add_u32 s28, s28, 0x40000
	s_addc_u32 s29, s29, 0
	s_mov_b32 m0, s36
	v_lshl_add_u64 v[222:223], s[28:29], 0, v[128:129]
	ds_read_b128 v[184:187], v151 offset:32768
	ds_read_b128 v[188:191], v151 offset:33792
	ds_read_b128 v[192:195], v151 offset:34816
	ds_read_b128 v[196:199], v151 offset:35840
	ds_read_b128 v[200:203], v151 offset:36864
	ds_read_b128 v[204:207], v151 offset:37888
	ds_read_b128 v[208:211], v151 offset:38912
	ds_read_b128 v[212:215], v151 offset:39936
	global_load_lds_dwordx4 v[222:223], off
	v_lshl_add_u64 v[222:223], s[28:29], 0, v[132:133]
	s_mov_b32 m0, s37
	s_nop 0
	global_load_lds_dwordx4 v[222:223], off
	s_waitcnt vmcnt(8)
	s_waitcnt lgkmcnt(0)
	s_barrier
	s_setprio 1
	s_waitcnt lgkmcnt(0)
	v_mfma_f32_16x16x32_bf16 v[124:127], v[152:155], v[184:187], v[124:127]
	v_mfma_f32_16x16x32_bf16 v[120:123], v[160:163], v[184:187], v[120:123]
	v_mfma_f32_16x16x32_bf16 v[108:111], v[152:155], v[192:195], v[108:111]
	v_mfma_f32_16x16x32_bf16 v[104:107], v[160:163], v[192:195], v[104:107]
	v_mfma_f32_16x16x32_bf16 v[92:95], v[152:155], v[200:203], v[92:95]
	v_mfma_f32_16x16x32_bf16 v[88:91], v[160:163], v[200:203], v[88:91]
	v_mfma_f32_16x16x32_bf16 v[76:79], v[152:155], v[208:211], v[76:79]
	v_mfma_f32_16x16x32_bf16 v[72:75], v[160:163], v[208:211], v[72:75]
	v_mfma_f32_16x16x32_bf16 v[124:127], v[156:159], v[188:191], v[124:127]
	v_mfma_f32_16x16x32_bf16 v[120:123], v[164:167], v[188:191], v[120:123]
	v_mfma_f32_16x16x32_bf16 v[108:111], v[156:159], v[196:199], v[108:111]
	v_mfma_f32_16x16x32_bf16 v[104:107], v[164:167], v[196:199], v[104:107]
	v_mfma_f32_16x16x32_bf16 v[92:95], v[156:159], v[204:207], v[92:95]
	v_mfma_f32_16x16x32_bf16 v[88:91], v[164:167], v[204:207], v[88:91]
	v_mfma_f32_16x16x32_bf16 v[76:79], v[156:159], v[212:215], v[76:79]
	v_mfma_f32_16x16x32_bf16 v[72:75], v[164:167], v[212:215], v[72:75]
	v_mfma_f32_16x16x32_bf16 v[116:119], v[168:171], v[184:187], v[116:119]
	v_mfma_f32_16x16x32_bf16 v[112:115], v[176:179], v[184:187], v[112:115]
	v_mfma_f32_16x16x32_bf16 v[100:103], v[168:171], v[192:195], v[100:103]
	v_mfma_f32_16x16x32_bf16 v[96:99], v[176:179], v[192:195], v[96:99]
	v_mfma_f32_16x16x32_bf16 v[84:87], v[168:171], v[200:203], v[84:87]
	v_mfma_f32_16x16x32_bf16 v[80:83], v[176:179], v[200:203], v[80:83]
	v_mfma_f32_16x16x32_bf16 v[68:71], v[168:171], v[208:211], v[68:71]
	v_mfma_f32_16x16x32_bf16 v[64:67], v[176:179], v[208:211], v[64:67]
	v_mfma_f32_16x16x32_bf16 v[116:119], v[172:175], v[188:191], v[116:119]
	v_mfma_f32_16x16x32_bf16 v[112:115], v[180:183], v[188:191], v[112:115]
	v_mfma_f32_16x16x32_bf16 v[100:103], v[172:175], v[196:199], v[100:103]
	v_mfma_f32_16x16x32_bf16 v[96:99], v[180:183], v[196:199], v[96:99]
	v_mfma_f32_16x16x32_bf16 v[84:87], v[172:175], v[204:207], v[84:87]
	v_mfma_f32_16x16x32_bf16 v[80:83], v[180:183], v[204:207], v[80:83]
	v_mfma_f32_16x16x32_bf16 v[68:71], v[172:175], v[212:215], v[68:71]
	v_mfma_f32_16x16x32_bf16 v[64:67], v[180:183], v[212:215], v[64:67]
	s_setprio 0
	s_barrier
; #define PG8_STAGE(bufoff, gbase, voff) do { _Pragma("unroll") for (int _i = 0; _i < 2; ++_i) \
;         __builtin_amdgcn_global_load_lds((const unsigned*)((const char*)(gbase) + (voff)[_i]), (PG8_LAS unsigned*)(lds + (bufoff) + ldsw + _i * 8192), 16, 0, 0); } while (0)
; #define PG8_LDA(dst, b, h) do { _Pragma("unroll") for (int m = 0; m < 4; ++m) _Pragma("unroll") for (int k = 0; k < 2; ++k) dst[m][k] = *(const PG8_LAS bf16x8*)(lds + PG8_SA(b, h) + aoff + m * 2048 + k * 1024); } while (0)
; #define PG8_MMA(ai, bj, At, Bt) do { __builtin_amdgcn_s_setprio(1); _Pragma("unroll") for (int m = 0; m < 4; ++m) _Pragma("unroll") for (int n = 0; n < 2; ++n) _Pragma("unroll") for (int k = 0; k < 2; ++k) \
;         acc[ai][bj][m][n] = __builtin_amdgcn_mfma_f32_16x16x32_bf16(Bt[n][k], At[m][k], acc[ai][bj][m][n], 0, 0, 0); __builtin_amdgcn_s_setprio(0); } while (0)
; #define PG8_WAIT_V(n) asm volatile("s_waitcnt vmcnt(" #n ")" ::: "memory")
; #define PG8_WAIT_L(n) asm volatile("s_waitcnt lgkmcnt(" #n ")" ::: "memory")
; #define PG8_BAR __builtin_amdgcn_s_barrier()
; #define PG8_SCHED __builtin_amdgcn_sched_barrier(0)
; template <class Epi, class Sched, bool ALIGN_EPI = false, bool SP2 = false>
; __device__ __forceinline__ void gemm_phase(PG8_LAS unsigned char* lds, const Gemm g, const Sched& S, const Epi& E, int wave_sgpr) {
;     ...
;         for (int t = 0; t < nt; t += 2) {
;             const bool last = (t == nt - 2);
;             const char* a1 = cA + (size_t)(t + 1) * kstep;
;             const char* a2 = last ? nA : cA + (size_t)(t + 2) * kstep; const char* b2 = last ? nB : cB + (size_t)(t + 2) * kstep;
;     ...
;             PG8_LDA(At, 1, 1); PG8_STAGE(PG8_SB(1, 0), b3, voffB); PG8_STAGE(PG8_SB(1, 1), b3 + hstepB, voffB); PG8_STAGE(PG8_SA(1, 0), a3, voffA);
;             PG8_WAIT_V(8); PG8_WAIT_L(0); PG8_BAR; PG8_MMA(1, 0, At, B0); PG8_MMA(1, 1, At, B1); PG8_BAR; PG8_SCHED;
	s_add_i32 s28, s51, s34
	v_lshl_add_u64 v[144:145], v[144:145], 0, s[8:9]
	s_mov_b32 m0, s28
	ds_read_b128 v[184:187], v151 offset:49152
	ds_read_b128 v[188:191], v151 offset:50176
	ds_read_b128 v[192:195], v151 offset:51200
	ds_read_b128 v[196:199], v151 offset:52224
	ds_read_b128 v[200:203], v151 offset:53248
	ds_read_b128 v[204:207], v151 offset:54272
	ds_read_b128 v[208:211], v151 offset:55296
	ds_read_b128 v[212:215], v151 offset:56320
	global_load_lds_dwordx4 v[144:145], off
	s_add_i32 m0, s28, 0x2000
	s_add_u32 s26, s26, 0x40080
	v_lshl_add_u64 v[144:145], v[216:217], 0, s[8:9]
	s_addc_u32 s27, s27, 0
	s_add_i32 s28, s52, s34
	global_load_lds_dwordx4 v[144:145], off
	v_lshl_add_u64 v[144:145], s[26:27], 0, v[130:131]
	s_mov_b32 m0, s28
	s_nop 0
	global_load_lds_dwordx4 v[144:145], off
	v_lshl_add_u64 v[144:145], s[26:27], 0, v[134:135]
	s_add_i32 m0, s28, 0x2000
	s_nop 0
	global_load_lds_dwordx4 v[144:145], off
	v_lshl_add_u64 v[144:145], v[218:219], 0, s[8:9]
	s_mov_b32 m0, s39
	s_nop 0
	global_load_lds_dwordx4 v[144:145], off
	v_lshl_add_u64 v[144:145], v[220:221], 0, s[8:9]
	s_mov_b32 m0, s40
	s_nop 0
	global_load_lds_dwordx4 v[144:145], off
	s_waitcnt vmcnt(8)
	s_waitcnt lgkmcnt(0)
	s_barrier
	s_setprio 1
	s_waitcnt lgkmcnt(0)
	v_mfma_f32_16x16x32_bf16 v[60:63], v[152:155], v[184:187], v[60:63]
	v_mfma_f32_16x16x32_bf16 v[56:59], v[160:163], v[184:187], v[56:59]
	v_mfma_f32_16x16x32_bf16 v[44:47], v[152:155], v[192:195], v[44:47]
	v_mfma_f32_16x16x32_bf16 v[40:43], v[160:163], v[192:195], v[40:43]
	v_mfma_f32_16x16x32_bf16 v[28:31], v[152:155], v[200:203], v[28:31]
	v_mfma_f32_16x16x32_bf16 v[24:27], v[160:163], v[200:203], v[24:27]
	v_mfma_f32_16x16x32_bf16 v[12:15], v[152:155], v[208:211], v[12:15]
	v_mfma_f32_16x16x32_bf16 v[8:11], v[160:163], v[208:211], v[8:11]
	v_mfma_f32_16x16x32_bf16 v[60:63], v[156:159], v[188:191], v[60:63]
	v_mfma_f32_16x16x32_bf16 v[56:59], v[164:167], v[188:191], v[56:59]
	v_mfma_f32_16x16x32_bf16 v[44:47], v[156:159], v[196:199], v[44:47]
	v_mfma_f32_16x16x32_bf16 v[40:43], v[164:167], v[196:199], v[40:43]
	v_mfma_f32_16x16x32_bf16 v[28:31], v[156:159], v[204:207], v[28:31]
	v_mfma_f32_16x16x32_bf16 v[24:27], v[164:167], v[204:207], v[24:27]
	v_mfma_f32_16x16x32_bf16 v[12:15], v[156:159], v[212:215], v[12:15]
	v_mfma_f32_16x16x32_bf16 v[8:11], v[164:167], v[212:215], v[8:11]
	v_mfma_f32_16x16x32_bf16 v[52:55], v[168:171], v[184:187], v[52:55]
	v_mfma_f32_16x16x32_bf16 v[48:51], v[176:179], v[184:187], v[48:51]
	v_mfma_f32_16x16x32_bf16 v[36:39], v[168:171], v[192:195], v[36:39]
	v_mfma_f32_16x16x32_bf16 v[32:35], v[176:179], v[192:195], v[32:35]
	v_mfma_f32_16x16x32_bf16 v[20:23], v[168:171], v[200:203], v[20:23]
	v_mfma_f32_16x16x32_bf16 v[16:19], v[176:179], v[200:203], v[16:19]
	v_mfma_f32_16x16x32_bf16 v[4:7], v[168:171], v[208:211], v[4:7]
	v_mfma_f32_16x16x32_bf16 v[0:3], v[176:179], v[208:211], v[0:3]
	v_mfma_f32_16x16x32_bf16 v[52:55], v[172:175], v[188:191], v[52:55]
	v_mfma_f32_16x16x32_bf16 v[48:51], v[180:183], v[188:191], v[48:51]
	v_mfma_f32_16x16x32_bf16 v[36:39], v[172:175], v[196:199], v[36:39]
	v_mfma_f32_16x16x32_bf16 v[32:35], v[180:183], v[196:199], v[32:35]
	v_mfma_f32_16x16x32_bf16 v[20:23], v[172:175], v[204:207], v[20:23]
	v_mfma_f32_16x16x32_bf16 v[16:19], v[180:183], v[204:207], v[16:19]
	v_mfma_f32_16x16x32_bf16 v[4:7], v[172:175], v[212:215], v[4:7]
	v_mfma_f32_16x16x32_bf16 v[0:3], v[180:183], v[212:215], v[0:3]
	s_setprio 0
	s_barrier
	s_add_i32 s50, s50, 2
	s_add_u32 s24, s24, 0x100
	s_addc_u32 s25, s25, 0
	s_add_u32 s48, s48, 0x100
	s_addc_u32 s49, s49, 0
	s_cmp_gt_u32 s50, 13
	s_cbranch_scc0 .LBB0_1855
	s_and_b64 vcc, exec, s[10:11]
	s_cbranch_vccz .LBB0_1858
	s_barrier

; #define PG8_STAGE(bufoff, gbase, voff) do { _Pragma("unroll") for (int _i = 0; _i < 2; ++_i) \
;         __builtin_amdgcn_global_load_lds((const unsigned*)((const char*)(gbase) + (voff)[_i]), (PG8_LAS unsigned*)(lds + (bufoff) + ldsw + _i * 8192), 16, 0, 0); } while (0)
; #define PG8_LDA(dst, b, h) do { _Pragma("unroll") for (int m = 0; m < 4; ++m) _Pragma("unroll") for (int k = 0; k < 2; ++k) dst[m][k] = *(const PG8_LAS bf16x8*)(lds + PG8_SA(b, h) + aoff + m * 2048 + k * 1024); } while (0)
; #define PG8_LDB(dst, b, h) do { _Pragma("unroll") for (int n = 0; n < 2; ++n) _Pragma("unroll") for (int k = 0; k < 2; ++k) dst[n][k] = *(const PG8_LAS bf16x8*)(lds + PG8_SB(b, h) + boff + n * 2048 + k * 1024); } while (0)
; #define PG8_MMA(ai, bj, At, Bt) do { __builtin_amdgcn_s_setprio(1); _Pragma("unroll") for (int m = 0; m < 4; ++m) _Pragma("unroll") for (int n = 0; n < 2; ++n) _Pragma("unroll") for (int k = 0; k < 2; ++k) \
;         acc[ai][bj][m][n] = __builtin_amdgcn_mfma_f32_16x16x32_bf16(Bt[n][k], At[m][k], acc[ai][bj][m][n], 0, 0, 0); __builtin_amdgcn_s_setprio(0); } while (0)
; #define PG8_WAIT_V(n) asm volatile("s_waitcnt vmcnt(" #n ")" ::: "memory")
; #define PG8_WAIT_L(n) asm volatile("s_waitcnt lgkmcnt(" #n ")" ::: "memory")
; #define PG8_BAR __builtin_amdgcn_s_barrier()
; #define PG8_SCHED __builtin_amdgcn_sched_barrier(0)
; template <class Epi, class Sched, bool ALIGN_EPI = false, bool SP2 = false>
; __device__ __forceinline__ void gemm_phase(PG8_LAS unsigned char* lds, const Gemm g, const Sched& S, const Epi& E, int wave_sgpr) {
;     ...
;             PG8_LDB(B0, 0, 0); PG8_LDB(B1, 0, 1); PG8_SCHED; PG8_LDA(At, 0, 0); PG8_STAGE(PG8_SA(1, 1), a1 + hstepA, voffA);
;             PG8_WAIT_V(8); PG8_WAIT_L(0); PG8_BAR; PG8_MMA(0, 0, At, B0); PG8_MMA(0, 1, At, B1); PG8_BAR; PG8_SCHED;
;             PG8_LDA(At, 0, 1); PG8_STAGE(PG8_SB(0, 0), b2, voffB); PG8_STAGE(PG8_SB(0, 1), b2 + hstepB, voffB); PG8_STAGE(PG8_SA(0, 0), a2, voffA);
.LBB0_1940:
	ds_read_b128 v[144:147], v155
	ds_read_b128 v[148:151], v155 offset:1024
	ds_read_b128 v[158:161], v155 offset:2048
	ds_read_b128 v[162:165], v155 offset:3072
	ds_read_b128 v[166:169], v156
	ds_read_b128 v[170:173], v156 offset:1024
	ds_read_b128 v[174:177], v156 offset:2048
	ds_read_b128 v[178:181], v156 offset:3072
	s_add_u32 s26, s24, 0x100
	s_addc_u32 s27, s25, 0
	s_cmp_eq_u32 s57, 40
	s_cselect_b32 s31, s5, s27
	s_cselect_b32 s30, s4, s26
	s_cselect_b32 s29, s23, s56
	s_cselect_b32 s28, s22, s55
	v_lshl_add_u64 v[214:215], s[24:25], 0, v[136:137]
	s_add_i32 m0, s37, 0xc000
	ds_read_b128 v[182:185], v157
	ds_read_b128 v[186:189], v157 offset:1024
	ds_read_b128 v[190:193], v157 offset:2048
	ds_read_b128 v[194:197], v157 offset:3072
	ds_read_b128 v[198:201], v157 offset:4096
	ds_read_b128 v[202:205], v157 offset:5120
	ds_read_b128 v[206:209], v157 offset:6144
	ds_read_b128 v[210:213], v157 offset:7168
	global_load_lds_dwordx4 v[214:215], off
	v_lshl_add_u64 v[214:215], s[24:25], 0, v[138:139]
	s_add_i32 m0, s37, 0xe000
	s_nop 0
	global_load_lds_dwordx4 v[214:215], off
	s_waitcnt vmcnt(8)
	s_waitcnt lgkmcnt(0)
	s_barrier
	s_setprio 1
	s_waitcnt lgkmcnt(0)
	v_mfma_f32_16x16x32_bf16 v[124:127], v[144:147], v[182:185], v[124:127]
	v_mfma_f32_16x16x32_bf16 v[120:123], v[158:161], v[182:185], v[120:123]
	v_mfma_f32_16x16x32_bf16 v[112:115], v[144:147], v[190:193], v[112:115]
	v_mfma_f32_16x16x32_bf16 v[104:107], v[158:161], v[190:193], v[104:107]
	v_mfma_f32_16x16x32_bf16 v[96:99], v[144:147], v[198:201], v[96:99]
	v_mfma_f32_16x16x32_bf16 v[88:91], v[158:161], v[198:201], v[88:91]
	v_mfma_f32_16x16x32_bf16 v[80:83], v[144:147], v[206:209], v[80:83]
	v_mfma_f32_16x16x32_bf16 v[72:75], v[158:161], v[206:209], v[72:75]
	v_mfma_f32_16x16x32_bf16 v[124:127], v[148:151], v[186:189], v[124:127]
	v_mfma_f32_16x16x32_bf16 v[120:123], v[162:165], v[186:189], v[120:123]
	v_mfma_f32_16x16x32_bf16 v[112:115], v[148:151], v[194:197], v[112:115]
	v_mfma_f32_16x16x32_bf16 v[104:107], v[162:165], v[194:197], v[104:107]
	v_mfma_f32_16x16x32_bf16 v[96:99], v[148:151], v[202:205], v[96:99]
	v_mfma_f32_16x16x32_bf16 v[88:91], v[162:165], v[202:205], v[88:91]
	v_mfma_f32_16x16x32_bf16 v[80:83], v[148:151], v[210:213], v[80:83]
	v_mfma_f32_16x16x32_bf16 v[72:75], v[162:165], v[210:213], v[72:75]
	v_mfma_f32_16x16x32_bf16 v[116:119], v[166:169], v[182:185], v[116:119]
	v_mfma_f32_16x16x32_bf16 v[108:111], v[174:177], v[182:185], v[108:111]
	v_mfma_f32_16x16x32_bf16 v[100:103], v[166:169], v[190:193], v[100:103]
	v_mfma_f32_16x16x32_bf16 v[92:95], v[174:177], v[190:193], v[92:95]
	v_mfma_f32_16x16x32_bf16 v[84:87], v[166:169], v[198:201], v[84:87]
	v_mfma_f32_16x16x32_bf16 v[76:79], v[174:177], v[198:201], v[76:79]
	v_mfma_f32_16x16x32_bf16 v[68:71], v[166:169], v[206:209], v[68:71]
	v_mfma_f32_16x16x32_bf16 v[64:67], v[174:177], v[206:209], v[64:67]
	v_mfma_f32_16x16x32_bf16 v[116:119], v[170:173], v[186:189], v[116:119]
	v_mfma_f32_16x16x32_bf16 v[108:111], v[178:181], v[186:189], v[108:111]
	v_mfma_f32_16x16x32_bf16 v[100:103], v[170:173], v[194:197], v[100:103]
	v_mfma_f32_16x16x32_bf16 v[92:95], v[178:181], v[194:197], v[92:95]
	v_mfma_f32_16x16x32_bf16 v[84:87], v[170:173], v[202:205], v[84:87]
	v_mfma_f32_16x16x32_bf16 v[76:79], v[178:181], v[202:205], v[76:79]
	v_mfma_f32_16x16x32_bf16 v[68:71], v[170:173], v[210:213], v[68:71]
	v_mfma_f32_16x16x32_bf16 v[64:67], v[178:181], v[210:213], v[64:67]
	s_setprio 0
	s_barrier
	s_add_i32 s24, s48, s36
	v_lshl_add_u64 v[214:215], s[28:29], 0, v[130:131]
	s_mov_b32 m0, s24
	ds_read_b128 v[182:185], v157 offset:16384
	ds_read_b128 v[186:189], v157 offset:17408
	ds_read_b128 v[190:193], v157 offset:18432
	ds_read_b128 v[194:197], v157 offset:19456
	ds_read_b128 v[198:201], v157 offset:20480
	ds_read_b128 v[202:205], v157 offset:21504
	ds_read_b128 v[206:209], v157 offset:22528
	ds_read_b128 v[210:213], v157 offset:23552
	global_load_lds_dwordx4 v[214:215], off
	s_add_i32 m0, s24, 0x2000
	s_add_u32 s24, s28, 0xb0000
	v_lshl_add_u64 v[216:217], s[28:29], 0, v[134:135]
	s_addc_u32 s25, s29, 0
	s_add_i32 s58, s49, s36
	global_load_lds_dwordx4 v[216:217], off
	v_lshl_add_u64 v[218:219], s[24:25], 0, v[130:131]
	s_mov_b32 m0, s58
	v_lshl_add_u64 v[220:221], s[30:31], 0, v[132:133]
	global_load_lds_dwordx4 v[218:219], off
	v_lshl_add_u64 v[218:219], s[24:25], 0, v[134:135]
	s_add_i32 m0, s58, 0x2000
	s_nop 0
	global_load_lds_dwordx4 v[218:219], off
	v_lshl_add_u64 v[218:219], s[30:31], 0, v[128:129]
	s_mov_b32 m0, s37
	s_nop 0
	global_load_lds_dwordx4 v[218:219], off
	s_mov_b32 m0, s38
	s_nop 0
	global_load_lds_dwordx4 v[220:221], off
	s_waitcnt vmcnt(8)
	s_waitcnt lgkmcnt(0)
	s_barrier
; #define PG8_STAGE(bufoff, gbase, voff) do { _Pragma("unroll") for (int _i = 0; _i < 2; ++_i) \
;         __builtin_amdgcn_global_load_lds((const unsigned*)((const char*)(gbase) + (voff)[_i]), (PG8_LAS unsigned*)(lds + (bufoff) + ldsw + _i * 8192), 16, 0, 0); } while (0)
; #define PG8_LDA(dst, b, h) do { _Pragma("unroll") for (int m = 0; m < 4; ++m) _Pragma("unroll") for (int k = 0; k < 2; ++k) dst[m][k] = *(const PG8_LAS bf16x8*)(lds + PG8_SA(b, h) + aoff + m * 2048 + k * 1024); } while (0)
; #define PG8_LDB(dst, b, h) do { _Pragma("unroll") for (int n = 0; n < 2; ++n) _Pragma("unroll") for (int k = 0; k < 2; ++k) dst[n][k] = *(const PG8_LAS bf16x8*)(lds + PG8_SB(b, h) + boff + n * 2048 + k * 1024); } while (0)
; #define PG8_MMA(ai, bj, At, Bt) do { __builtin_amdgcn_s_setprio(1); _Pragma("unroll") for (int m = 0; m < 4; ++m) _Pragma("unroll") for (int n = 0; n < 2; ++n) _Pragma("unroll") for (int k = 0; k < 2; ++k) \
;         acc[ai][bj][m][n] = __builtin_amdgcn_mfma_f32_16x16x32_bf16(Bt[n][k], At[m][k], acc[ai][bj][m][n], 0, 0, 0); __builtin_amdgcn_s_setprio(0); } while (0)
; #define PG8_WAIT_V(n) asm volatile("s_waitcnt vmcnt(" #n ")" ::: "memory")
; #define PG8_WAIT_L(n) asm volatile("s_waitcnt lgkmcnt(" #n ")" ::: "memory")
; #define PG8_BAR __builtin_amdgcn_s_barrier()
; #define PG8_SCHED __builtin_amdgcn_sched_barrier(0)
; template <class Epi, class Sched, bool ALIGN_EPI = false, bool SP2 = false>
; __device__ __forceinline__ void gemm_phase(PG8_LAS unsigned char* lds, const Gemm g, const Sched& S, const Epi& E, int wave_sgpr) {
;     ...
;             PG8_WAIT_V(8); PG8_WAIT_L(0); PG8_BAR; PG8_MMA(1, 0, At, B0); PG8_MMA(1, 1, At, B1); PG8_BAR; PG8_SCHED;
;             PG8_LDB(B0, 1, 0); PG8_LDB(B1, 1, 1); PG8_SCHED; PG8_LDA(At, 1, 0); PG8_STAGE(PG8_SA(0, 1), a2 + hstepA, voffA);
;             PG8_WAIT_V(8); PG8_WAIT_L(0); PG8_BAR; PG8_MMA(0, 0, At, B0); PG8_MMA(0, 1, At, B1); PG8_BAR; PG8_SCHED;
	s_setprio 1
	s_waitcnt lgkmcnt(0)
	v_mfma_f32_16x16x32_bf16 v[60:63], v[144:147], v[182:185], v[60:63]
	v_mfma_f32_16x16x32_bf16 v[56:59], v[158:161], v[182:185], v[56:59]
	v_mfma_f32_16x16x32_bf16 v[48:51], v[144:147], v[190:193], v[48:51]
	v_mfma_f32_16x16x32_bf16 v[40:43], v[158:161], v[190:193], v[40:43]
	v_mfma_f32_16x16x32_bf16 v[32:35], v[144:147], v[198:201], v[32:35]
	v_mfma_f32_16x16x32_bf16 v[24:27], v[158:161], v[198:201], v[24:27]
	v_mfma_f32_16x16x32_bf16 v[16:19], v[144:147], v[206:209], v[16:19]
	v_mfma_f32_16x16x32_bf16 v[8:11], v[158:161], v[206:209], v[8:11]
	v_mfma_f32_16x16x32_bf16 v[60:63], v[148:151], v[186:189], v[60:63]
	v_mfma_f32_16x16x32_bf16 v[56:59], v[162:165], v[186:189], v[56:59]
	v_mfma_f32_16x16x32_bf16 v[48:51], v[148:151], v[194:197], v[48:51]
	v_mfma_f32_16x16x32_bf16 v[40:43], v[162:165], v[194:197], v[40:43]
	v_mfma_f32_16x16x32_bf16 v[32:35], v[148:151], v[202:205], v[32:35]
	v_mfma_f32_16x16x32_bf16 v[24:27], v[162:165], v[202:205], v[24:27]
	v_mfma_f32_16x16x32_bf16 v[16:19], v[148:151], v[210:213], v[16:19]
	v_mfma_f32_16x16x32_bf16 v[8:11], v[162:165], v[210:213], v[8:11]
	v_mfma_f32_16x16x32_bf16 v[52:55], v[166:169], v[182:185], v[52:55]
	v_mfma_f32_16x16x32_bf16 v[44:47], v[174:177], v[182:185], v[44:47]
	v_mfma_f32_16x16x32_bf16 v[36:39], v[166:169], v[190:193], v[36:39]
	v_mfma_f32_16x16x32_bf16 v[28:31], v[174:177], v[190:193], v[28:31]
	v_mfma_f32_16x16x32_bf16 v[20:23], v[166:169], v[198:201], v[20:23]
	v_mfma_f32_16x16x32_bf16 v[12:15], v[174:177], v[198:201], v[12:15]
	v_mfma_f32_16x16x32_bf16 v[4:7], v[166:169], v[206:209], v[4:7]
	v_mfma_f32_16x16x32_bf16 v[0:3], v[174:177], v[206:209], v[0:3]
	v_mfma_f32_16x16x32_bf16 v[52:55], v[170:173], v[186:189], v[52:55]
	v_mfma_f32_16x16x32_bf16 v[44:47], v[178:181], v[186:189], v[44:47]
	v_mfma_f32_16x16x32_bf16 v[36:39], v[170:173], v[194:197], v[36:39]
	v_mfma_f32_16x16x32_bf16 v[28:31], v[178:181], v[194:197], v[28:31]
	v_mfma_f32_16x16x32_bf16 v[20:23], v[170:173], v[202:205], v[20:23]
	v_mfma_f32_16x16x32_bf16 v[12:15], v[178:181], v[202:205], v[12:15]
	v_mfma_f32_16x16x32_bf16 v[4:7], v[170:173], v[210:213], v[4:7]
	v_mfma_f32_16x16x32_bf16 v[0:3], v[178:181], v[210:213], v[0:3]
	s_setprio 0
	s_barrier
	s_add_i32 s58, 0, 0x18000
	s_add_i32 s59, 0, 0x1c000
	v_add_u32_e32 v162, s58, v153
	v_add_u32_e32 v178, s59, v153
	ds_read_b128 v[144:147], v162
	ds_read_b128 v[148:151], v162 offset:1024
	ds_read_b128 v[158:161], v162 offset:2048
	ds_read_b128 v[162:165], v162 offset:3072
	ds_read_b128 v[166:169], v178
	ds_read_b128 v[170:173], v178 offset:1024
	ds_read_b128 v[174:177], v178 offset:2048
	ds_read_b128 v[178:181], v178 offset:3072
	s_add_u32 s24, s30, 0xb0000
	s_addc_u32 s25, s31, 0
	s_mov_b32 m0, s39
	v_lshl_add_u64 v[222:223], s[24:25], 0, v[128:129]
	ds_read_b128 v[182:185], v157 offset:32768
	ds_read_b128 v[186:189], v157 offset:33792
	ds_read_b128 v[190:193], v157 offset:34816
	ds_read_b128 v[194:197], v157 offset:35840
	ds_read_b128 v[198:201], v157 offset:36864
	ds_read_b128 v[202:205], v157 offset:37888
	ds_read_b128 v[206:209], v157 offset:38912
	ds_read_b128 v[210:213], v157 offset:39936
	global_load_lds_dwordx4 v[222:223], off
	v_lshl_add_u64 v[222:223], s[24:25], 0, v[132:133]
	s_mov_b32 m0, s40
	s_nop 0
	global_load_lds_dwordx4 v[222:223], off
	s_waitcnt vmcnt(8)
	s_waitcnt lgkmcnt(0)
	s_barrier
	s_setprio 1
	s_waitcnt lgkmcnt(0)
	v_mfma_f32_16x16x32_bf16 v[124:127], v[144:147], v[182:185], v[124:127]
	v_mfma_f32_16x16x32_bf16 v[120:123], v[158:161], v[182:185], v[120:123]
	v_mfma_f32_16x16x32_bf16 v[112:115], v[144:147], v[190:193], v[112:115]
	v_mfma_f32_16x16x32_bf16 v[104:107], v[158:161], v[190:193], v[104:107]
	v_mfma_f32_16x16x32_bf16 v[96:99], v[144:147], v[198:201], v[96:99]
	v_mfma_f32_16x16x32_bf16 v[88:91], v[158:161], v[198:201], v[88:91]
	v_mfma_f32_16x16x32_bf16 v[80:83], v[144:147], v[206:209], v[80:83]
	v_mfma_f32_16x16x32_bf16 v[72:75], v[158:161], v[206:209], v[72:75]
	v_mfma_f32_16x16x32_bf16 v[124:127], v[148:151], v[186:189], v[124:127]
	v_mfma_f32_16x16x32_bf16 v[120:123], v[162:165], v[186:189], v[120:123]
	v_mfma_f32_16x16x32_bf16 v[112:115], v[148:151], v[194:197], v[112:115]
	v_mfma_f32_16x16x32_bf16 v[104:107], v[162:165], v[194:197], v[104:107]
	v_mfma_f32_16x16x32_bf16 v[96:99], v[148:151], v[202:205], v[96:99]
	v_mfma_f32_16x16x32_bf16 v[88:91], v[162:165], v[202:205], v[88:91]
	v_mfma_f32_16x16x32_bf16 v[80:83], v[148:151], v[210:213], v[80:83]
	v_mfma_f32_16x16x32_bf16 v[72:75], v[162:165], v[210:213], v[72:75]
	v_mfma_f32_16x16x32_bf16 v[116:119], v[166:169], v[182:185], v[116:119]
	v_mfma_f32_16x16x32_bf16 v[108:111], v[174:177], v[182:185], v[108:111]
	v_mfma_f32_16x16x32_bf16 v[100:103], v[166:169], v[190:193], v[100:103]
	v_mfma_f32_16x16x32_bf16 v[92:95], v[174:177], v[190:193], v[92:95]
	v_mfma_f32_16x16x32_bf16 v[84:87], v[166:169], v[198:201], v[84:87]
	v_mfma_f32_16x16x32_bf16 v[76:79], v[174:177], v[198:201], v[76:79]
	v_mfma_f32_16x16x32_bf16 v[68:71], v[166:169], v[206:209], v[68:71]
	v_mfma_f32_16x16x32_bf16 v[64:67], v[174:177], v[206:209], v[64:67]
	v_mfma_f32_16x16x32_bf16 v[116:119], v[170:173], v[186:189], v[116:119]
	v_mfma_f32_16x16x32_bf16 v[108:111], v[178:181], v[186:189], v[108:111]
	v_mfma_f32_16x16x32_bf16 v[100:103], v[170:173], v[194:197], v[100:103]
	v_mfma_f32_16x16x32_bf16 v[92:95], v[178:181], v[194:197], v[92:95]
	v_mfma_f32_16x16x32_bf16 v[84:87], v[170:173], v[202:205], v[84:87]
	v_mfma_f32_16x16x32_bf16 v[76:79], v[178:181], v[202:205], v[76:79]
	v_mfma_f32_16x16x32_bf16 v[68:71], v[170:173], v[210:213], v[68:71]
	v_mfma_f32_16x16x32_bf16 v[64:67], v[178:181], v[210:213], v[64:67]
	s_setprio 0
	s_barrier
; #define PG8_STAGE(bufoff, gbase, voff) do { _Pragma("unroll") for (int _i = 0; _i < 2; ++_i) \
;         __builtin_amdgcn_global_load_lds((const unsigned*)((const char*)(gbase) + (voff)[_i]), (PG8_LAS unsigned*)(lds + (bufoff) + ldsw + _i * 8192), 16, 0, 0); } while (0)
; #define PG8_LDA(dst, b, h) do { _Pragma("unroll") for (int m = 0; m < 4; ++m) _Pragma("unroll") for (int k = 0; k < 2; ++k) dst[m][k] = *(const PG8_LAS bf16x8*)(lds + PG8_SA(b, h) + aoff + m * 2048 + k * 1024); } while (0)
; #define PG8_MMA(ai, bj, At, Bt) do { __builtin_amdgcn_s_setprio(1); _Pragma("unroll") for (int m = 0; m < 4; ++m) _Pragma("unroll") for (int n = 0; n < 2; ++n) _Pragma("unroll") for (int k = 0; k < 2; ++k) \
;         acc[ai][bj][m][n] = __builtin_amdgcn_mfma_f32_16x16x32_bf16(Bt[n][k], At[m][k], acc[ai][bj][m][n], 0, 0, 0); __builtin_amdgcn_s_setprio(0); } while (0)
; #define PG8_WAIT_V(n) asm volatile("s_waitcnt vmcnt(" #n ")" ::: "memory")
; #define PG8_WAIT_L(n) asm volatile("s_waitcnt lgkmcnt(" #n ")" ::: "memory")
; #define PG8_BAR __builtin_amdgcn_s_barrier()
; #define PG8_SCHED __builtin_amdgcn_sched_barrier(0)
; template <class Epi, class Sched, bool ALIGN_EPI = false, bool SP2 = false>
; __device__ __forceinline__ void gemm_phase(PG8_LAS unsigned char* lds, const Gemm g, const Sched& S, const Epi& E, int wave_sgpr) {
;     ...
;         for (int t = 0; t < nt; t += 2) {
;             const bool last = (t == nt - 2);
;             const char* a1 = cA + (size_t)(t + 1) * kstep;
;             const char* a2 = last ? nA : cA + (size_t)(t + 2) * kstep; const char* b2 = last ? nB : cB + (size_t)(t + 2) * kstep;
;     ...
;             PG8_LDA(At, 1, 1); PG8_STAGE(PG8_SB(1, 0), b3, voffB); PG8_STAGE(PG8_SB(1, 1), b3 + hstepB, voffB); PG8_STAGE(PG8_SA(1, 0), a3, voffA);
;             PG8_WAIT_V(8); PG8_WAIT_L(0); PG8_BAR; PG8_MMA(1, 0, At, B0); PG8_MMA(1, 1, At, B1); PG8_BAR; PG8_SCHED;
	s_add_i32 s24, s58, s36
	v_lshl_add_u64 v[214:215], v[214:215], 0, s[14:15]
	s_mov_b32 m0, s24
	ds_read_b128 v[182:185], v157 offset:49152
	ds_read_b128 v[186:189], v157 offset:50176
	ds_read_b128 v[190:193], v157 offset:51200
	ds_read_b128 v[194:197], v157 offset:52224
	ds_read_b128 v[198:201], v157 offset:53248
	ds_read_b128 v[202:205], v157 offset:54272
	ds_read_b128 v[206:209], v157 offset:55296
	ds_read_b128 v[210:213], v157 offset:56320
	global_load_lds_dwordx4 v[214:215], off
	s_add_i32 m0, s24, 0x2000
	s_add_u32 s24, s28, 0xb0080
	v_lshl_add_u64 v[214:215], v[216:217], 0, s[14:15]
	s_addc_u32 s25, s29, 0
	s_add_i32 s28, s59, s36
	global_load_lds_dwordx4 v[214:215], off
	v_lshl_add_u64 v[214:215], s[24:25], 0, v[130:131]
	s_mov_b32 m0, s28
	s_nop 0
	global_load_lds_dwordx4 v[214:215], off
	v_lshl_add_u64 v[214:215], s[24:25], 0, v[134:135]
	s_add_i32 m0, s28, 0x2000
	s_nop 0
	global_load_lds_dwordx4 v[214:215], off
	v_lshl_add_u64 v[214:215], v[218:219], 0, s[14:15]
	s_mov_b32 m0, s45
	s_nop 0
	global_load_lds_dwordx4 v[214:215], off
	v_lshl_add_u64 v[214:215], v[220:221], 0, s[14:15]
	s_mov_b32 m0, s46
	s_nop 0
	global_load_lds_dwordx4 v[214:215], off
	s_waitcnt vmcnt(8)
	s_waitcnt lgkmcnt(0)
	s_barrier
	s_setprio 1
	s_waitcnt lgkmcnt(0)
	v_mfma_f32_16x16x32_bf16 v[60:63], v[144:147], v[182:185], v[60:63]
	v_mfma_f32_16x16x32_bf16 v[56:59], v[158:161], v[182:185], v[56:59]
	v_mfma_f32_16x16x32_bf16 v[48:51], v[144:147], v[190:193], v[48:51]
	v_mfma_f32_16x16x32_bf16 v[40:43], v[158:161], v[190:193], v[40:43]
	v_mfma_f32_16x16x32_bf16 v[32:35], v[144:147], v[198:201], v[32:35]
	v_mfma_f32_16x16x32_bf16 v[24:27], v[158:161], v[198:201], v[24:27]
	v_mfma_f32_16x16x32_bf16 v[16:19], v[144:147], v[206:209], v[16:19]
	v_mfma_f32_16x16x32_bf16 v[8:11], v[158:161], v[206:209], v[8:11]
	v_mfma_f32_16x16x32_bf16 v[60:63], v[148:151], v[186:189], v[60:63]
	v_mfma_f32_16x16x32_bf16 v[56:59], v[162:165], v[186:189], v[56:59]
	v_mfma_f32_16x16x32_bf16 v[48:51], v[148:151], v[194:197], v[48:51]
	v_mfma_f32_16x16x32_bf16 v[40:43], v[162:165], v[194:197], v[40:43]
	v_mfma_f32_16x16x32_bf16 v[32:35], v[148:151], v[202:205], v[32:35]
	v_mfma_f32_16x16x32_bf16 v[24:27], v[162:165], v[202:205], v[24:27]
	v_mfma_f32_16x16x32_bf16 v[16:19], v[148:151], v[210:213], v[16:19]
	v_mfma_f32_16x16x32_bf16 v[8:11], v[162:165], v[210:213], v[8:11]
	v_mfma_f32_16x16x32_bf16 v[52:55], v[166:169], v[182:185], v[52:55]
	v_mfma_f32_16x16x32_bf16 v[44:47], v[174:177], v[182:185], v[44:47]
	v_mfma_f32_16x16x32_bf16 v[36:39], v[166:169], v[190:193], v[36:39]
	v_mfma_f32_16x16x32_bf16 v[28:31], v[174:177], v[190:193], v[28:31]
	v_mfma_f32_16x16x32_bf16 v[20:23], v[166:169], v[198:201], v[20:23]
	v_mfma_f32_16x16x32_bf16 v[12:15], v[174:177], v[198:201], v[12:15]
	v_mfma_f32_16x16x32_bf16 v[4:7], v[166:169], v[206:209], v[4:7]
	v_mfma_f32_16x16x32_bf16 v[0:3], v[174:177], v[206:209], v[0:3]
	v_mfma_f32_16x16x32_bf16 v[52:55], v[170:173], v[186:189], v[52:55]
	v_mfma_f32_16x16x32_bf16 v[44:47], v[178:181], v[186:189], v[44:47]
	v_mfma_f32_16x16x32_bf16 v[36:39], v[170:173], v[194:197], v[36:39]
	v_mfma_f32_16x16x32_bf16 v[28:31], v[178:181], v[194:197], v[28:31]
	v_mfma_f32_16x16x32_bf16 v[20:23], v[170:173], v[202:205], v[20:23]
	v_mfma_f32_16x16x32_bf16 v[12:15], v[178:181], v[202:205], v[12:15]
	v_mfma_f32_16x16x32_bf16 v[4:7], v[170:173], v[210:213], v[4:7]
	v_mfma_f32_16x16x32_bf16 v[0:3], v[178:181], v[210:213], v[0:3]
	s_setprio 0
	s_barrier
	s_add_i32 s57, s57, 2
	s_add_u32 s55, s55, 0x100
	s_addc_u32 s56, s56, 0
	s_cmp_gt_u32 s57, 41
	s_mov_b64 s[24:25], s[26:27]
	s_cbranch_scc0 .LBB0_1940
	s_and_b64 vcc, exec, s[16:17]
	s_cbranch_vccz .LBB0_1943
	s_barrier
